# speedup vs baseline: 1.0249x; 1.0007x over previous
; __device__ __forceinline__ float sigmf(float x) { return 1.f / (1.f + __expf(-x)); }
; template <int MT, int NT, class F>
; __device__ __forceinline__ void acc_foreach(int tid, f32x16 (&acc)[MT][NT], F f) {
;     ...
; #pragma unroll
;   for (int mt = 0; mt < MT; mt++)
; #pragma unroll
;     for (int nt = 0; nt < NT; nt++)
; #pragma unroll
;       for (int i = 0; i < 16; i++) {
;         int row = wm * (MT * 32) + mt * 32 + (i & 3) + 8 * (i >> 2) + 4 * hi;
;         int col = wn * (NT * 32) + nt * 32 + c;
;         f(row, col, acc[mt][nt][i]);
;         if (i == 15) __builtin_amdgcn_sched_barrier(0);
;       }
; __device__ __forceinline__ void inproj_epilogue(const Params& p, int layer, int mt, int ntile, int tid,
;                                                 f32x16 (&acc)[2][2], unsigned char* smem) {
;     ...
;     acc_foreach(tid, acc, [&](int row, int col, float v) {
;       int t = m0 + row;
;       float o = v;
;       if (mode == 1) o = (t >= NPADR) ? v : 0.f;
;       if (mode == 2) o = sigmf(v);
;       sT[row * 136 + col] = f2bf(o);
;     });
.Lfp_0:
	v_bfe_u32 v110, v16, 16, 1
	v_and_b32_e32 v106, 0x5f, v106
	v_add3_u32 v111, v16, v110, s77
	v_mul_lo_u32 v110, v96, s78
	v_lshl_add_u32 v107, v106, 1, v110
	ds_write_b16_d16_hi v107, v111
	v_bfe_u32 v112, v17, 16, 1
	v_add3_u32 v112, v17, v112, s77
	v_add_u32_e32 v111, 0x110, v110
	v_lshl_add_u32 v110, v106, 1, v111
	ds_write_b16_d16_hi v110, v112
	v_bfe_u32 v113, v18, 16, 1
	v_add3_u32 v113, v18, v113, s77
	v_add_u32_e32 v112, 0x110, v111
	v_lshl_add_u32 v111, v106, 1, v112
	ds_write_b16_d16_hi v111, v113
	v_bfe_u32 v114, v19, 16, 1
	v_add3_u32 v114, v19, v114, s77
	v_add_u32_e32 v113, 0x110, v112
	v_lshl_add_u32 v112, v106, 1, v113
	ds_write_b16_d16_hi v112, v114
	v_bfe_u32 v115, v20, 16, 1
	v_add3_u32 v115, v20, v115, s77
	v_add_u32_e32 v114, 0x550, v113
	v_lshl_add_u32 v113, v106, 1, v114
	ds_write_b16_d16_hi v113, v115
	v_bfe_u32 v116, v21, 16, 1
	v_add3_u32 v116, v21, v116, s77
	v_add_u32_e32 v115, 0x110, v114
	v_lshl_add_u32 v114, v106, 1, v115
	ds_write_b16_d16_hi v114, v116
	v_bfe_u32 v117, v22, 16, 1
	v_add3_u32 v117, v22, v117, s77
	v_add_u32_e32 v116, 0x110, v115
	v_lshl_add_u32 v115, v106, 1, v116
	ds_write_b16_d16_hi v115, v117
	v_bfe_u32 v118, v23, 16, 1
	v_add_u32_e32 v116, 0x110, v116
	v_add3_u32 v118, v23, v118, s77
	v_lshl_add_u32 v117, v106, 1, v116
	ds_write_b16_d16_hi v117, v118
	v_bfe_u32 v119, v24, 16, 1
	v_add_u32_e32 v116, 0x550, v116
	v_add3_u32 v119, v24, v119, s77
	v_lshl_add_u32 v118, v106, 1, v116
	ds_write_b16_d16_hi v118, v119
	v_bfe_u32 v120, v25, 16, 1
	v_add_u32_e32 v116, 0x110, v116
	v_add3_u32 v120, v25, v120, s77
	v_lshl_add_u32 v119, v106, 1, v116
	ds_write_b16_d16_hi v119, v120
	v_bfe_u32 v121, v26, 16, 1
	v_add_u32_e32 v116, 0x110, v116
	v_add3_u32 v121, v26, v121, s77
	v_lshl_add_u32 v120, v106, 1, v116
	ds_write_b16_d16_hi v120, v121
	v_bfe_u32 v122, v27, 16, 1
	v_add_u32_e32 v116, 0x110, v116
	v_add3_u32 v122, v27, v122, s77
	v_lshl_add_u32 v121, v106, 1, v116
	ds_write_b16_d16_hi v121, v122
	v_bfe_u32 v123, v28, 16, 1
	v_add_u32_e32 v116, 0x550, v116
	v_add3_u32 v123, v28, v123, s77
	v_lshl_add_u32 v122, v106, 1, v116
	ds_write_b16_d16_hi v122, v123
	v_bfe_u32 v124, v29, 16, 1
	v_add_u32_e32 v116, 0x110, v116
	v_add3_u32 v124, v29, v124, s77
	v_lshl_add_u32 v123, v106, 1, v116
	ds_write_b16_d16_hi v123, v124
	v_bfe_u32 v125, v30, 16, 1
	v_add_u32_e32 v116, 0x110, v116
	v_add3_u32 v124, v30, v125, s77
	v_lshl_add_u32 v116, v106, 1, v116
	ds_write_b16_d16_hi v116, v124
	v_bfe_u32 v125, v31, 16, 1
	v_add3_u32 v124, v31, v125, s77
	ds_write_b16_d16_hi v116, v124 offset:272
	v_bfe_u32 v124, v48, 16, 1
	v_add3_u32 v48, v48, v124, s77
	ds_write_b16_d16_hi v107, v48 offset:64
	v_bfe_u32 v48, v49, 16, 1
	v_add3_u32 v48, v49, v48, s77
	ds_write_b16_d16_hi v110, v48 offset:64
	v_bfe_u32 v49, v50, 16, 1
	v_add3_u32 v48, v50, v49, s77
	ds_write_b16_d16_hi v111, v48 offset:64
	v_bfe_u32 v49, v51, 16, 1
	v_add3_u32 v48, v51, v49, s77
	ds_write_b16_d16_hi v112, v48 offset:64
	v_bfe_u32 v49, v52, 16, 1
	v_add3_u32 v48, v52, v49, s77
	ds_write_b16_d16_hi v113, v48 offset:64
	v_bfe_u32 v49, v53, 16, 1
	v_add3_u32 v48, v53, v49, s77
	ds_write_b16_d16_hi v114, v48 offset:64
	v_bfe_u32 v49, v54, 16, 1
	v_add3_u32 v48, v54, v49, s77
	ds_write_b16_d16_hi v115, v48 offset:64
	v_bfe_u32 v49, v55, 16, 1
	v_add3_u32 v48, v55, v49, s77
	ds_write_b16_d16_hi v117, v48 offset:64
	v_bfe_u32 v49, v56, 16, 1
	v_add3_u32 v48, v56, v49, s77
	ds_write_b16_d16_hi v118, v48 offset:64
	v_bfe_u32 v49, v57, 16, 1
	v_add3_u32 v48, v57, v49, s77
	ds_write_b16_d16_hi v119, v48 offset:64
	v_bfe_u32 v49, v58, 16, 1
	v_add3_u32 v48, v58, v49, s77
	ds_write_b16_d16_hi v120, v48 offset:64
	v_bfe_u32 v49, v59, 16, 1
	v_add3_u32 v48, v59, v49, s77
	ds_write_b16_d16_hi v121, v48 offset:64
	v_bfe_u32 v49, v60, 16, 1
	v_add3_u32 v48, v60, v49, s77
	ds_write_b16_d16_hi v122, v48 offset:64
	v_bfe_u32 v49, v61, 16, 1
	v_add3_u32 v48, v61, v49, s77
	ds_write_b16_d16_hi v123, v48 offset:64
	v_bfe_u32 v49, v62, 16, 1
	v_add3_u32 v48, v62, v49, s77
	ds_write_b16_d16_hi v116, v48 offset:64
	v_bfe_u32 v50, v63, 16, 1
; __device__ __forceinline__ float sigmf(float x) { return 1.f / (1.f + __expf(-x)); }
; template <int MT, int NT, class F>
; __device__ __forceinline__ void acc_foreach(int tid, f32x16 (&acc)[MT][NT], F f) {
;     ...
; #pragma unroll
;   for (int mt = 0; mt < MT; mt++)
; #pragma unroll
;     for (int nt = 0; nt < NT; nt++)
; #pragma unroll
;       for (int i = 0; i < 16; i++) {
;         int row = wm * (MT * 32) + mt * 32 + (i & 3) + 8 * (i >> 2) + 4 * hi;
;         int col = wn * (NT * 32) + nt * 32 + c;
;         f(row, col, acc[mt][nt][i]);
;         if (i == 15) __builtin_amdgcn_sched_barrier(0);
;       }
; __device__ __forceinline__ void inproj_epilogue(const Params& p, int layer, int mt, int ntile, int tid,
;                                                 f32x16 (&acc)[2][2], unsigned char* smem) {
;     ...
;     acc_foreach(tid, acc, [&](int row, int col, float v) {
;       int t = m0 + row;
;       float o = v;
;       if (mode == 1) o = (t >= NPADR) ? v : 0.f;
;       if (mode == 2) o = sigmf(v);
;       sT[row * 136 + col] = f2bf(o);
;     });
	v_add_u32_e32 v49, 0x110, v116
	v_add3_u32 v48, v63, v50, s77
	ds_write_b16_d16_hi v49, v48 offset:64
	v_or_b32_e32 v48, 32, v96
	v_add_u32_e32 v49, s60, v48
	v_cmp_lt_i32_e64 s[8:9], s43, v49
	v_bfe_u32 v50, v0, 16, 1
	v_add3_u32 v50, v0, v50, s77
	v_mul_lo_u32 v49, v48, s78
	v_lshl_add_u32 v48, v106, 1, v49
	ds_write_b16_d16_hi v48, v50
	v_bfe_u32 v51, v1, 16, 1
	v_add3_u32 v51, v1, v51, s77
	v_add_u32_e32 v50, 0x110, v49
	v_lshl_add_u32 v49, v106, 1, v50
	ds_write_b16_d16_hi v49, v51
	v_bfe_u32 v52, v2, 16, 1
	v_add3_u32 v52, v2, v52, s77
	v_add_u32_e32 v51, 0x110, v50
	v_lshl_add_u32 v50, v106, 1, v51
	ds_write_b16_d16_hi v50, v52
	v_bfe_u32 v53, v3, 16, 1
	v_add3_u32 v53, v3, v53, s77
	v_add_u32_e32 v52, 0x110, v51
	v_lshl_add_u32 v51, v106, 1, v52
	ds_write_b16_d16_hi v51, v53
	v_bfe_u32 v54, v4, 16, 1
	v_add3_u32 v54, v4, v54, s77
	v_add_u32_e32 v53, 0x550, v52
	v_lshl_add_u32 v52, v106, 1, v53
	ds_write_b16_d16_hi v52, v54
	v_bfe_u32 v55, v5, 16, 1
	v_add3_u32 v55, v5, v55, s77
	v_add_u32_e32 v54, 0x110, v53
	v_lshl_add_u32 v53, v106, 1, v54
	ds_write_b16_d16_hi v53, v55
	v_bfe_u32 v56, v6, 16, 1
	v_add3_u32 v56, v6, v56, s77
	v_add_u32_e32 v55, 0x110, v54
	v_lshl_add_u32 v54, v106, 1, v55
	ds_write_b16_d16_hi v54, v56
	v_bfe_u32 v57, v7, 16, 1
	v_add_u32_e32 v55, 0x110, v55
	v_add3_u32 v57, v7, v57, s77
	v_lshl_add_u32 v56, v106, 1, v55
	ds_write_b16_d16_hi v56, v57
	v_bfe_u32 v58, v8, 16, 1
	v_add_u32_e32 v55, 0x550, v55
	v_add3_u32 v58, v8, v58, s77
	v_lshl_add_u32 v57, v106, 1, v55
	ds_write_b16_d16_hi v57, v58
	v_bfe_u32 v59, v9, 16, 1
	v_add_u32_e32 v55, 0x110, v55
	v_add3_u32 v59, v9, v59, s77
	v_lshl_add_u32 v58, v106, 1, v55
	ds_write_b16_d16_hi v58, v59
	v_bfe_u32 v60, v10, 16, 1
	v_add_u32_e32 v55, 0x110, v55
	v_add3_u32 v60, v10, v60, s77
	v_lshl_add_u32 v59, v106, 1, v55
	ds_write_b16_d16_hi v59, v60
	v_bfe_u32 v61, v11, 16, 1
	v_add_u32_e32 v55, 0x110, v55
	v_add3_u32 v61, v11, v61, s77
	v_lshl_add_u32 v60, v106, 1, v55
	ds_write_b16_d16_hi v60, v61
	v_bfe_u32 v62, v12, 16, 1
	v_add_u32_e32 v55, 0x550, v55
	v_add3_u32 v62, v12, v62, s77
	v_lshl_add_u32 v61, v106, 1, v55
	ds_write_b16_d16_hi v61, v62
	v_bfe_u32 v63, v13, 16, 1
	v_add_u32_e32 v55, 0x110, v55
	v_add3_u32 v63, v13, v63, s77
	v_lshl_add_u32 v62, v106, 1, v55
	ds_write_b16_d16_hi v62, v63
	v_bfe_u32 v107, v14, 16, 1
	v_add_u32_e32 v55, 0x110, v55
	v_add3_u32 v63, v14, v107, s77
	v_lshl_add_u32 v55, v106, 1, v55
	ds_write_b16_d16_hi v55, v63
	v_bfe_u32 v96, v15, 16, 1
	v_add3_u32 v63, v15, v96, s77
	ds_write_b16_d16_hi v55, v63 offset:272
	v_bfe_u32 v63, v32, 16, 1
	v_add3_u32 v32, v32, v63, s77
	ds_write_b16_d16_hi v48, v32 offset:64
	v_bfe_u32 v32, v33, 16, 1
	v_add3_u32 v32, v33, v32, s77
	ds_write_b16_d16_hi v49, v32 offset:64
	v_bfe_u32 v33, v34, 16, 1
	v_add3_u32 v32, v34, v33, s77
	ds_write_b16_d16_hi v50, v32 offset:64
	v_bfe_u32 v33, v35, 16, 1
	v_add3_u32 v32, v35, v33, s77
	ds_write_b16_d16_hi v51, v32 offset:64
	v_bfe_u32 v33, v36, 16, 1
	v_add3_u32 v32, v36, v33, s77
	ds_write_b16_d16_hi v52, v32 offset:64
	v_bfe_u32 v33, v37, 16, 1
	v_add3_u32 v32, v37, v33, s77
	ds_write_b16_d16_hi v53, v32 offset:64
	v_bfe_u32 v33, v38, 16, 1
	v_add3_u32 v32, v38, v33, s77
	ds_write_b16_d16_hi v54, v32 offset:64
	v_bfe_u32 v33, v39, 16, 1
	v_add3_u32 v32, v39, v33, s77
	ds_write_b16_d16_hi v56, v32 offset:64
	v_bfe_u32 v33, v40, 16, 1
	v_add3_u32 v32, v40, v33, s77
	ds_write_b16_d16_hi v57, v32 offset:64
	v_bfe_u32 v33, v41, 16, 1
	v_add3_u32 v32, v41, v33, s77
	ds_write_b16_d16_hi v58, v32 offset:64
	v_bfe_u32 v33, v42, 16, 1
	v_add3_u32 v32, v42, v33, s77
	ds_write_b16_d16_hi v59, v32 offset:64
	v_bfe_u32 v33, v43, 16, 1
	v_add3_u32 v32, v43, v33, s77
	ds_write_b16_d16_hi v60, v32 offset:64
	v_bfe_u32 v33, v44, 16, 1
	v_add3_u32 v32, v44, v33, s77
	ds_write_b16_d16_hi v61, v32 offset:64
	v_bfe_u32 v33, v45, 16, 1
	v_add3_u32 v32, v45, v33, s77
	ds_write_b16_d16_hi v62, v32 offset:64
	v_bfe_u32 v33, v46, 16, 1
	v_add3_u32 v32, v46, v33, s77
	ds_write_b16_d16_hi v55, v32 offset:64
	v_mov_b32_e32 v32, v47
	s_branch .LBB0_398

; __device__ __forceinline__ float sigmf(float x) { return 1.f / (1.f + __expf(-x)); }
; template <int MT, int NT, class F>
; __device__ __forceinline__ void acc_foreach(int tid, f32x16 (&acc)[MT][NT], F f) {
;     ...
; #pragma unroll
;   for (int mt = 0; mt < MT; mt++)
; #pragma unroll
;     for (int nt = 0; nt < NT; nt++)
; #pragma unroll
;       for (int i = 0; i < 16; i++) {
;         int row = wm * (MT * 32) + mt * 32 + (i & 3) + 8 * (i >> 2) + 4 * hi;
;         int col = wn * (NT * 32) + nt * 32 + c;
;         f(row, col, acc[mt][nt][i]);
;         if (i == 15) __builtin_amdgcn_sched_barrier(0);
;       }
; __device__ __forceinline__ void inproj_epilogue(const Params& p, int layer, int mt, int ntile, int tid,
;                                                 f32x16 (&acc)[2][2], unsigned char* smem) {
;     ...
;     acc_foreach(tid, acc, [&](int row, int col, float v) {
;       int t = m0 + row;
;       float o = v;
;       if (mode == 1) o = (t >= NPADR) ? v : 0.f;
;       if (mode == 2) o = sigmf(v);
;       sT[row * 136 + col] = f2bf(o);
;     });
.Lfp_1:
	v_bfe_u32 v110, v16, 16, 1
	v_and_b32_e32 v106, 0x5f, v106
	v_add3_u32 v111, v16, v110, s78
	v_mul_lo_u32 v110, v96, s79
	v_lshl_add_u32 v107, v106, 1, v110
	ds_write_b16_d16_hi v107, v111
	v_bfe_u32 v112, v17, 16, 1
	v_add3_u32 v112, v17, v112, s78
	v_add_u32_e32 v111, 0x110, v110
	v_lshl_add_u32 v110, v106, 1, v111
	ds_write_b16_d16_hi v110, v112
	v_bfe_u32 v113, v18, 16, 1
	v_add3_u32 v113, v18, v113, s78
	v_add_u32_e32 v112, 0x110, v111
	v_lshl_add_u32 v111, v106, 1, v112
	ds_write_b16_d16_hi v111, v113
	v_bfe_u32 v114, v19, 16, 1
	v_add3_u32 v114, v19, v114, s78
	v_add_u32_e32 v113, 0x110, v112
	v_lshl_add_u32 v112, v106, 1, v113
	ds_write_b16_d16_hi v112, v114
	v_bfe_u32 v115, v20, 16, 1
	v_add3_u32 v115, v20, v115, s78
	v_add_u32_e32 v114, 0x550, v113
	v_lshl_add_u32 v113, v106, 1, v114
	ds_write_b16_d16_hi v113, v115
	v_bfe_u32 v116, v21, 16, 1
	v_add3_u32 v116, v21, v116, s78
	v_add_u32_e32 v115, 0x110, v114
	v_lshl_add_u32 v114, v106, 1, v115
	ds_write_b16_d16_hi v114, v116
	v_bfe_u32 v117, v22, 16, 1
	v_add3_u32 v117, v22, v117, s78
	v_add_u32_e32 v116, 0x110, v115
	v_lshl_add_u32 v115, v106, 1, v116
	ds_write_b16_d16_hi v115, v117
	v_bfe_u32 v118, v23, 16, 1
	v_add_u32_e32 v116, 0x110, v116
	v_add3_u32 v118, v23, v118, s78
	v_lshl_add_u32 v117, v106, 1, v116
	ds_write_b16_d16_hi v117, v118
	v_bfe_u32 v119, v24, 16, 1
	v_add_u32_e32 v116, 0x550, v116
	v_add3_u32 v119, v24, v119, s78
	v_lshl_add_u32 v118, v106, 1, v116
	ds_write_b16_d16_hi v118, v119
	v_bfe_u32 v120, v25, 16, 1
	v_add_u32_e32 v116, 0x110, v116
	v_add3_u32 v120, v25, v120, s78
	v_lshl_add_u32 v119, v106, 1, v116
	ds_write_b16_d16_hi v119, v120
	v_bfe_u32 v121, v26, 16, 1
	v_add_u32_e32 v116, 0x110, v116
	v_add3_u32 v121, v26, v121, s78
	v_lshl_add_u32 v120, v106, 1, v116
	ds_write_b16_d16_hi v120, v121
	v_bfe_u32 v122, v27, 16, 1
	v_add_u32_e32 v116, 0x110, v116
	v_add3_u32 v122, v27, v122, s78
	v_lshl_add_u32 v121, v106, 1, v116
	ds_write_b16_d16_hi v121, v122
	v_bfe_u32 v123, v28, 16, 1
	v_add_u32_e32 v116, 0x550, v116
	v_add3_u32 v123, v28, v123, s78
	v_lshl_add_u32 v122, v106, 1, v116
	ds_write_b16_d16_hi v122, v123
	v_bfe_u32 v124, v29, 16, 1
	v_add_u32_e32 v116, 0x110, v116
	v_add3_u32 v124, v29, v124, s78
	v_lshl_add_u32 v123, v106, 1, v116
	ds_write_b16_d16_hi v123, v124
	v_bfe_u32 v125, v30, 16, 1
	v_add_u32_e32 v116, 0x110, v116
	v_add3_u32 v124, v30, v125, s78
	v_lshl_add_u32 v116, v106, 1, v116
	ds_write_b16_d16_hi v116, v124
	v_bfe_u32 v125, v31, 16, 1
	v_add3_u32 v124, v31, v125, s78
	ds_write_b16_d16_hi v116, v124 offset:272
	v_bfe_u32 v124, v48, 16, 1
	v_add3_u32 v48, v48, v124, s78
	ds_write_b16_d16_hi v107, v48 offset:64
	v_bfe_u32 v48, v49, 16, 1
	v_add3_u32 v48, v49, v48, s78
	ds_write_b16_d16_hi v110, v48 offset:64
	v_bfe_u32 v49, v50, 16, 1
	v_add3_u32 v48, v50, v49, s78
	ds_write_b16_d16_hi v111, v48 offset:64
	v_bfe_u32 v49, v51, 16, 1
	v_add3_u32 v48, v51, v49, s78
	ds_write_b16_d16_hi v112, v48 offset:64
	v_bfe_u32 v49, v52, 16, 1
	v_add3_u32 v48, v52, v49, s78
	ds_write_b16_d16_hi v113, v48 offset:64
	v_bfe_u32 v49, v53, 16, 1
	v_add3_u32 v48, v53, v49, s78
	ds_write_b16_d16_hi v114, v48 offset:64
	v_bfe_u32 v49, v54, 16, 1
	v_add3_u32 v48, v54, v49, s78
	ds_write_b16_d16_hi v115, v48 offset:64
	v_bfe_u32 v49, v55, 16, 1
	v_add3_u32 v48, v55, v49, s78
	ds_write_b16_d16_hi v117, v48 offset:64
	v_bfe_u32 v49, v56, 16, 1
	v_add3_u32 v48, v56, v49, s78
	ds_write_b16_d16_hi v118, v48 offset:64
	v_bfe_u32 v49, v57, 16, 1
	v_add3_u32 v48, v57, v49, s78
	ds_write_b16_d16_hi v119, v48 offset:64
	v_bfe_u32 v49, v58, 16, 1
	v_add3_u32 v48, v58, v49, s78
	ds_write_b16_d16_hi v120, v48 offset:64
	v_bfe_u32 v49, v59, 16, 1
	v_add3_u32 v48, v59, v49, s78
	ds_write_b16_d16_hi v121, v48 offset:64
	v_bfe_u32 v49, v60, 16, 1
	v_add3_u32 v48, v60, v49, s78
	ds_write_b16_d16_hi v122, v48 offset:64
	v_bfe_u32 v49, v61, 16, 1
	v_add3_u32 v48, v61, v49, s78
	ds_write_b16_d16_hi v123, v48 offset:64
	v_bfe_u32 v49, v62, 16, 1
	v_add3_u32 v48, v62, v49, s78
	ds_write_b16_d16_hi v116, v48 offset:64
	v_bfe_u32 v50, v63, 16, 1
; __device__ __forceinline__ float sigmf(float x) { return 1.f / (1.f + __expf(-x)); }
; template <int MT, int NT, class F>
; __device__ __forceinline__ void acc_foreach(int tid, f32x16 (&acc)[MT][NT], F f) {
;     ...
; #pragma unroll
;   for (int mt = 0; mt < MT; mt++)
; #pragma unroll
;     for (int nt = 0; nt < NT; nt++)
; #pragma unroll
;       for (int i = 0; i < 16; i++) {
;         int row = wm * (MT * 32) + mt * 32 + (i & 3) + 8 * (i >> 2) + 4 * hi;
;         int col = wn * (NT * 32) + nt * 32 + c;
;         f(row, col, acc[mt][nt][i]);
;         if (i == 15) __builtin_amdgcn_sched_barrier(0);
;       }
; __device__ __forceinline__ void inproj_epilogue(const Params& p, int layer, int mt, int ntile, int tid,
;                                                 f32x16 (&acc)[2][2], unsigned char* smem) {
;     ...
;     acc_foreach(tid, acc, [&](int row, int col, float v) {
;       int t = m0 + row;
;       float o = v;
;       if (mode == 1) o = (t >= NPADR) ? v : 0.f;
;       if (mode == 2) o = sigmf(v);
;       sT[row * 136 + col] = f2bf(o);
;     });
	v_add_u32_e32 v49, 0x110, v116
	v_add3_u32 v48, v63, v50, s78
	ds_write_b16_d16_hi v49, v48 offset:64
	v_or_b32_e32 v48, 32, v96
	v_add_u32_e32 v49, s90, v48
	v_cmp_lt_i32_e64 s[8:9], s76, v49
	v_bfe_u32 v50, v0, 16, 1
	v_add3_u32 v50, v0, v50, s78
	v_mul_lo_u32 v49, v48, s79
	v_lshl_add_u32 v48, v106, 1, v49
	ds_write_b16_d16_hi v48, v50
	v_bfe_u32 v51, v1, 16, 1
	v_add3_u32 v51, v1, v51, s78
	v_add_u32_e32 v50, 0x110, v49
	v_lshl_add_u32 v49, v106, 1, v50
	ds_write_b16_d16_hi v49, v51
	v_bfe_u32 v52, v2, 16, 1
	v_add3_u32 v52, v2, v52, s78
	v_add_u32_e32 v51, 0x110, v50
	v_lshl_add_u32 v50, v106, 1, v51
	ds_write_b16_d16_hi v50, v52
	v_bfe_u32 v53, v3, 16, 1
	v_add3_u32 v53, v3, v53, s78
	v_add_u32_e32 v52, 0x110, v51
	v_lshl_add_u32 v51, v106, 1, v52
	ds_write_b16_d16_hi v51, v53
	v_bfe_u32 v54, v4, 16, 1
	v_add3_u32 v54, v4, v54, s78
	v_add_u32_e32 v53, 0x550, v52
	v_lshl_add_u32 v52, v106, 1, v53
	ds_write_b16_d16_hi v52, v54
	v_bfe_u32 v55, v5, 16, 1
	v_add3_u32 v55, v5, v55, s78
	v_add_u32_e32 v54, 0x110, v53
	v_lshl_add_u32 v53, v106, 1, v54
	ds_write_b16_d16_hi v53, v55
	v_bfe_u32 v56, v6, 16, 1
	v_add3_u32 v56, v6, v56, s78
	v_add_u32_e32 v55, 0x110, v54
	v_lshl_add_u32 v54, v106, 1, v55
	ds_write_b16_d16_hi v54, v56
	v_bfe_u32 v57, v7, 16, 1
	v_add_u32_e32 v55, 0x110, v55
	v_add3_u32 v57, v7, v57, s78
	v_lshl_add_u32 v56, v106, 1, v55
	ds_write_b16_d16_hi v56, v57
	v_bfe_u32 v58, v8, 16, 1
	v_add_u32_e32 v55, 0x550, v55
	v_add3_u32 v58, v8, v58, s78
	v_lshl_add_u32 v57, v106, 1, v55
	ds_write_b16_d16_hi v57, v58
	v_bfe_u32 v59, v9, 16, 1
	v_add_u32_e32 v55, 0x110, v55
	v_add3_u32 v59, v9, v59, s78
	v_lshl_add_u32 v58, v106, 1, v55
	ds_write_b16_d16_hi v58, v59
	v_bfe_u32 v60, v10, 16, 1
	v_add_u32_e32 v55, 0x110, v55
	v_add3_u32 v60, v10, v60, s78
	v_lshl_add_u32 v59, v106, 1, v55
	ds_write_b16_d16_hi v59, v60
	v_bfe_u32 v61, v11, 16, 1
	v_add_u32_e32 v55, 0x110, v55
	v_add3_u32 v61, v11, v61, s78
	v_lshl_add_u32 v60, v106, 1, v55
	ds_write_b16_d16_hi v60, v61
	v_bfe_u32 v62, v12, 16, 1
	v_add_u32_e32 v55, 0x550, v55
	v_add3_u32 v62, v12, v62, s78
	v_lshl_add_u32 v61, v106, 1, v55
	ds_write_b16_d16_hi v61, v62
	v_bfe_u32 v63, v13, 16, 1
	v_add_u32_e32 v55, 0x110, v55
	v_add3_u32 v63, v13, v63, s78
	v_lshl_add_u32 v62, v106, 1, v55
	ds_write_b16_d16_hi v62, v63
	v_bfe_u32 v107, v14, 16, 1
	v_add_u32_e32 v55, 0x110, v55
	v_add3_u32 v63, v14, v107, s78
	v_lshl_add_u32 v55, v106, 1, v55
	ds_write_b16_d16_hi v55, v63
	v_bfe_u32 v96, v15, 16, 1
	v_add3_u32 v63, v15, v96, s78
	ds_write_b16_d16_hi v55, v63 offset:272
	v_bfe_u32 v63, v32, 16, 1
	v_add3_u32 v32, v32, v63, s78
	ds_write_b16_d16_hi v48, v32 offset:64
	v_bfe_u32 v32, v33, 16, 1
	v_add3_u32 v32, v33, v32, s78
	ds_write_b16_d16_hi v49, v32 offset:64
	v_bfe_u32 v33, v34, 16, 1
	v_add3_u32 v32, v34, v33, s78
	ds_write_b16_d16_hi v50, v32 offset:64
	v_bfe_u32 v33, v35, 16, 1
	v_add3_u32 v32, v35, v33, s78
	ds_write_b16_d16_hi v51, v32 offset:64
	v_bfe_u32 v33, v36, 16, 1
	v_add3_u32 v32, v36, v33, s78
	ds_write_b16_d16_hi v52, v32 offset:64
	v_bfe_u32 v33, v37, 16, 1
	v_add3_u32 v32, v37, v33, s78
	ds_write_b16_d16_hi v53, v32 offset:64
	v_bfe_u32 v33, v38, 16, 1
	v_add3_u32 v32, v38, v33, s78
	ds_write_b16_d16_hi v54, v32 offset:64
	v_bfe_u32 v33, v39, 16, 1
	v_add3_u32 v32, v39, v33, s78
	ds_write_b16_d16_hi v56, v32 offset:64
	v_bfe_u32 v33, v40, 16, 1
	v_add3_u32 v32, v40, v33, s78
	ds_write_b16_d16_hi v57, v32 offset:64
	v_bfe_u32 v33, v41, 16, 1
	v_add3_u32 v32, v41, v33, s78
	ds_write_b16_d16_hi v58, v32 offset:64
	v_bfe_u32 v33, v42, 16, 1
	v_add3_u32 v32, v42, v33, s78
	ds_write_b16_d16_hi v59, v32 offset:64
	v_bfe_u32 v33, v43, 16, 1
	v_add3_u32 v32, v43, v33, s78
	ds_write_b16_d16_hi v60, v32 offset:64
	v_bfe_u32 v33, v44, 16, 1
	v_add3_u32 v32, v44, v33, s78
	ds_write_b16_d16_hi v61, v32 offset:64
	v_bfe_u32 v33, v45, 16, 1
	v_add3_u32 v32, v45, v33, s78
	ds_write_b16_d16_hi v62, v32 offset:64
	v_bfe_u32 v33, v46, 16, 1
	v_add3_u32 v32, v46, v33, s78
	ds_write_b16_d16_hi v55, v32 offset:64
	v_mov_b32_e32 v32, v47
	s_branch .LBB0_717

; __device__ __forceinline__ float sigmf(float x) { return 1.f / (1.f + __expf(-x)); }
; template <int MT, int NT, class F>
; __device__ __forceinline__ void acc_foreach(int tid, f32x16 (&acc)[MT][NT], F f) {
;     ...
; #pragma unroll
;   for (int mt = 0; mt < MT; mt++)
; #pragma unroll
;     for (int nt = 0; nt < NT; nt++)
; #pragma unroll
;       for (int i = 0; i < 16; i++) {
;         int row = wm * (MT * 32) + mt * 32 + (i & 3) + 8 * (i >> 2) + 4 * hi;
;         int col = wn * (NT * 32) + nt * 32 + c;
;         f(row, col, acc[mt][nt][i]);
;         if (i == 15) __builtin_amdgcn_sched_barrier(0);
;       }
; __device__ __forceinline__ void inproj_epilogue(const Params& p, int layer, int mt, int ntile, int tid,
;                                                 f32x16 (&acc)[2][2], unsigned char* smem) {
;     ...
;     acc_foreach(tid, acc, [&](int row, int col, float v) {
;       int t = m0 + row;
;       float o = v;
;       if (mode == 1) o = (t >= NPADR) ? v : 0.f;
;       if (mode == 2) o = sigmf(v);
;       sT[row * 136 + col] = f2bf(o);
;     });
.Lfp_2:
	v_bfe_u32 v110, v16, 16, 1
	v_and_b32_e32 v106, 0x5f, v106
	v_add3_u32 v111, v16, v110, s79
	v_mul_lo_u32 v110, v96, s80
	v_lshl_add_u32 v107, v106, 1, v110
	ds_write_b16_d16_hi v107, v111
	v_bfe_u32 v112, v17, 16, 1
	v_add3_u32 v112, v17, v112, s79
	v_add_u32_e32 v111, 0x110, v110
	v_lshl_add_u32 v110, v106, 1, v111
	ds_write_b16_d16_hi v110, v112
	v_bfe_u32 v113, v18, 16, 1
	v_add3_u32 v113, v18, v113, s79
	v_add_u32_e32 v112, 0x110, v111
	v_lshl_add_u32 v111, v106, 1, v112
	ds_write_b16_d16_hi v111, v113
	v_bfe_u32 v114, v19, 16, 1
	v_add3_u32 v114, v19, v114, s79
	v_add_u32_e32 v113, 0x110, v112
	v_lshl_add_u32 v112, v106, 1, v113
	ds_write_b16_d16_hi v112, v114
	v_bfe_u32 v115, v20, 16, 1
	v_add3_u32 v115, v20, v115, s79
	v_add_u32_e32 v114, 0x550, v113
	v_lshl_add_u32 v113, v106, 1, v114
	ds_write_b16_d16_hi v113, v115
	v_bfe_u32 v116, v21, 16, 1
	v_add3_u32 v116, v21, v116, s79
	v_add_u32_e32 v115, 0x110, v114
	v_lshl_add_u32 v114, v106, 1, v115
	ds_write_b16_d16_hi v114, v116
	v_bfe_u32 v117, v22, 16, 1
	v_add3_u32 v117, v22, v117, s79
	v_add_u32_e32 v116, 0x110, v115
	v_lshl_add_u32 v115, v106, 1, v116
	ds_write_b16_d16_hi v115, v117
	v_bfe_u32 v118, v23, 16, 1
	v_add_u32_e32 v116, 0x110, v116
	v_add3_u32 v118, v23, v118, s79
	v_lshl_add_u32 v117, v106, 1, v116
	ds_write_b16_d16_hi v117, v118
	v_bfe_u32 v119, v24, 16, 1
	v_add_u32_e32 v116, 0x550, v116
	v_add3_u32 v119, v24, v119, s79
	v_lshl_add_u32 v118, v106, 1, v116
	ds_write_b16_d16_hi v118, v119
	v_bfe_u32 v120, v25, 16, 1
	v_add_u32_e32 v116, 0x110, v116
	v_add3_u32 v120, v25, v120, s79
	v_lshl_add_u32 v119, v106, 1, v116
	ds_write_b16_d16_hi v119, v120
	v_bfe_u32 v121, v26, 16, 1
	v_add_u32_e32 v116, 0x110, v116
	v_add3_u32 v121, v26, v121, s79
	v_lshl_add_u32 v120, v106, 1, v116
	ds_write_b16_d16_hi v120, v121
	v_bfe_u32 v122, v27, 16, 1
	v_add_u32_e32 v116, 0x110, v116
	v_add3_u32 v122, v27, v122, s79
	v_lshl_add_u32 v121, v106, 1, v116
	ds_write_b16_d16_hi v121, v122
	v_bfe_u32 v123, v28, 16, 1
	v_add_u32_e32 v116, 0x550, v116
	v_add3_u32 v123, v28, v123, s79
	v_lshl_add_u32 v122, v106, 1, v116
	ds_write_b16_d16_hi v122, v123
	v_bfe_u32 v124, v29, 16, 1
	v_add_u32_e32 v116, 0x110, v116
	v_add3_u32 v124, v29, v124, s79
	v_lshl_add_u32 v123, v106, 1, v116
	ds_write_b16_d16_hi v123, v124
	v_bfe_u32 v125, v30, 16, 1
	v_add_u32_e32 v116, 0x110, v116
	v_add3_u32 v124, v30, v125, s79
	v_lshl_add_u32 v116, v106, 1, v116
	ds_write_b16_d16_hi v116, v124
	v_bfe_u32 v125, v31, 16, 1
	v_add3_u32 v124, v31, v125, s79
	ds_write_b16_d16_hi v116, v124 offset:272
	v_bfe_u32 v124, v48, 16, 1
	v_add3_u32 v48, v48, v124, s79
	ds_write_b16_d16_hi v107, v48 offset:64
	v_bfe_u32 v48, v49, 16, 1
	v_add3_u32 v48, v49, v48, s79
	ds_write_b16_d16_hi v110, v48 offset:64
	v_bfe_u32 v49, v50, 16, 1
	v_add3_u32 v48, v50, v49, s79
	ds_write_b16_d16_hi v111, v48 offset:64
	v_bfe_u32 v49, v51, 16, 1
	v_add3_u32 v48, v51, v49, s79
	ds_write_b16_d16_hi v112, v48 offset:64
	v_bfe_u32 v49, v52, 16, 1
	v_add3_u32 v48, v52, v49, s79
	ds_write_b16_d16_hi v113, v48 offset:64
	v_bfe_u32 v49, v53, 16, 1
	v_add3_u32 v48, v53, v49, s79
	ds_write_b16_d16_hi v114, v48 offset:64
	v_bfe_u32 v49, v54, 16, 1
	v_add3_u32 v48, v54, v49, s79
	ds_write_b16_d16_hi v115, v48 offset:64
	v_bfe_u32 v49, v55, 16, 1
	v_add3_u32 v48, v55, v49, s79
	ds_write_b16_d16_hi v117, v48 offset:64
	v_bfe_u32 v49, v56, 16, 1
	v_add3_u32 v48, v56, v49, s79
	ds_write_b16_d16_hi v118, v48 offset:64
	v_bfe_u32 v49, v57, 16, 1
	v_add3_u32 v48, v57, v49, s79
	ds_write_b16_d16_hi v119, v48 offset:64
	v_bfe_u32 v49, v58, 16, 1
	v_add3_u32 v48, v58, v49, s79
	ds_write_b16_d16_hi v120, v48 offset:64
	v_bfe_u32 v49, v59, 16, 1
	v_add3_u32 v48, v59, v49, s79
	ds_write_b16_d16_hi v121, v48 offset:64
	v_bfe_u32 v49, v60, 16, 1
	v_add3_u32 v48, v60, v49, s79
	ds_write_b16_d16_hi v122, v48 offset:64
	v_bfe_u32 v49, v61, 16, 1
	v_add3_u32 v48, v61, v49, s79
	ds_write_b16_d16_hi v123, v48 offset:64
	v_bfe_u32 v49, v62, 16, 1
	v_add3_u32 v48, v62, v49, s79
	ds_write_b16_d16_hi v116, v48 offset:64
	v_bfe_u32 v50, v63, 16, 1
; __device__ __forceinline__ float sigmf(float x) { return 1.f / (1.f + __expf(-x)); }
; template <int MT, int NT, class F>
; __device__ __forceinline__ void acc_foreach(int tid, f32x16 (&acc)[MT][NT], F f) {
;     ...
; #pragma unroll
;   for (int mt = 0; mt < MT; mt++)
; #pragma unroll
;     for (int nt = 0; nt < NT; nt++)
; #pragma unroll
;       for (int i = 0; i < 16; i++) {
;         int row = wm * (MT * 32) + mt * 32 + (i & 3) + 8 * (i >> 2) + 4 * hi;
;         int col = wn * (NT * 32) + nt * 32 + c;
;         f(row, col, acc[mt][nt][i]);
;         if (i == 15) __builtin_amdgcn_sched_barrier(0);
;       }
; __device__ __forceinline__ void inproj_epilogue(const Params& p, int layer, int mt, int ntile, int tid,
;                                                 f32x16 (&acc)[2][2], unsigned char* smem) {
;     ...
;     acc_foreach(tid, acc, [&](int row, int col, float v) {
;       int t = m0 + row;
;       float o = v;
;       if (mode == 1) o = (t >= NPADR) ? v : 0.f;
;       if (mode == 2) o = sigmf(v);
;       sT[row * 136 + col] = f2bf(o);
;     });
	v_add_u32_e32 v49, 0x110, v116
	v_add3_u32 v48, v63, v50, s79
	ds_write_b16_d16_hi v49, v48 offset:64
	v_or_b32_e32 v48, 32, v96
	v_add_u32_e32 v49, s0, v48
	v_cmp_lt_i32_e64 s[8:9], s77, v49
	v_bfe_u32 v50, v0, 16, 1
	v_add3_u32 v50, v0, v50, s79
	v_mul_lo_u32 v49, v48, s80
	v_lshl_add_u32 v48, v106, 1, v49
	ds_write_b16_d16_hi v48, v50
	v_bfe_u32 v51, v1, 16, 1
	v_add3_u32 v51, v1, v51, s79
	v_add_u32_e32 v50, 0x110, v49
	v_lshl_add_u32 v49, v106, 1, v50
	ds_write_b16_d16_hi v49, v51
	v_bfe_u32 v52, v2, 16, 1
	v_add3_u32 v52, v2, v52, s79
	v_add_u32_e32 v51, 0x110, v50
	v_lshl_add_u32 v50, v106, 1, v51
	ds_write_b16_d16_hi v50, v52
	v_bfe_u32 v53, v3, 16, 1
	v_add3_u32 v53, v3, v53, s79
	v_add_u32_e32 v52, 0x110, v51
	v_lshl_add_u32 v51, v106, 1, v52
	ds_write_b16_d16_hi v51, v53
	v_bfe_u32 v54, v4, 16, 1
	v_add3_u32 v54, v4, v54, s79
	v_add_u32_e32 v53, 0x550, v52
	v_lshl_add_u32 v52, v106, 1, v53
	ds_write_b16_d16_hi v52, v54
	v_bfe_u32 v55, v5, 16, 1
	v_add3_u32 v55, v5, v55, s79
	v_add_u32_e32 v54, 0x110, v53
	v_lshl_add_u32 v53, v106, 1, v54
	ds_write_b16_d16_hi v53, v55
	v_bfe_u32 v56, v6, 16, 1
	v_add3_u32 v56, v6, v56, s79
	v_add_u32_e32 v55, 0x110, v54
	v_lshl_add_u32 v54, v106, 1, v55
	ds_write_b16_d16_hi v54, v56
	v_bfe_u32 v57, v7, 16, 1
	v_add_u32_e32 v55, 0x110, v55
	v_add3_u32 v57, v7, v57, s79
	v_lshl_add_u32 v56, v106, 1, v55
	ds_write_b16_d16_hi v56, v57
	v_bfe_u32 v58, v8, 16, 1
	v_add_u32_e32 v55, 0x550, v55
	v_add3_u32 v58, v8, v58, s79
	v_lshl_add_u32 v57, v106, 1, v55
	ds_write_b16_d16_hi v57, v58
	v_bfe_u32 v59, v9, 16, 1
	v_add_u32_e32 v55, 0x110, v55
	v_add3_u32 v59, v9, v59, s79
	v_lshl_add_u32 v58, v106, 1, v55
	ds_write_b16_d16_hi v58, v59
	v_bfe_u32 v60, v10, 16, 1
	v_add_u32_e32 v55, 0x110, v55
	v_add3_u32 v60, v10, v60, s79
	v_lshl_add_u32 v59, v106, 1, v55
	ds_write_b16_d16_hi v59, v60
	v_bfe_u32 v61, v11, 16, 1
	v_add_u32_e32 v55, 0x110, v55
	v_add3_u32 v61, v11, v61, s79
	v_lshl_add_u32 v60, v106, 1, v55
	ds_write_b16_d16_hi v60, v61
	v_bfe_u32 v62, v12, 16, 1
	v_add_u32_e32 v55, 0x550, v55
	v_add3_u32 v62, v12, v62, s79
	v_lshl_add_u32 v61, v106, 1, v55
	ds_write_b16_d16_hi v61, v62
	v_bfe_u32 v63, v13, 16, 1
	v_add_u32_e32 v55, 0x110, v55
	v_add3_u32 v63, v13, v63, s79
	v_lshl_add_u32 v62, v106, 1, v55
	ds_write_b16_d16_hi v62, v63
	v_bfe_u32 v107, v14, 16, 1
	v_add_u32_e32 v55, 0x110, v55
	v_add3_u32 v63, v14, v107, s79
	v_lshl_add_u32 v55, v106, 1, v55
	ds_write_b16_d16_hi v55, v63
	v_bfe_u32 v96, v15, 16, 1
	v_add3_u32 v63, v15, v96, s79
	ds_write_b16_d16_hi v55, v63 offset:272
	v_bfe_u32 v63, v32, 16, 1
	v_add3_u32 v32, v32, v63, s79
	ds_write_b16_d16_hi v48, v32 offset:64
	v_bfe_u32 v32, v33, 16, 1
	v_add3_u32 v32, v33, v32, s79
	ds_write_b16_d16_hi v49, v32 offset:64
	v_bfe_u32 v33, v34, 16, 1
	v_add3_u32 v32, v34, v33, s79
	ds_write_b16_d16_hi v50, v32 offset:64
	v_bfe_u32 v33, v35, 16, 1
	v_add3_u32 v32, v35, v33, s79
	ds_write_b16_d16_hi v51, v32 offset:64
	v_bfe_u32 v33, v36, 16, 1
	v_add3_u32 v32, v36, v33, s79
	ds_write_b16_d16_hi v52, v32 offset:64
	v_bfe_u32 v33, v37, 16, 1
	v_add3_u32 v32, v37, v33, s79
	ds_write_b16_d16_hi v53, v32 offset:64
	v_bfe_u32 v33, v38, 16, 1
	v_add3_u32 v32, v38, v33, s79
	ds_write_b16_d16_hi v54, v32 offset:64
	v_bfe_u32 v33, v39, 16, 1
	v_add3_u32 v32, v39, v33, s79
	ds_write_b16_d16_hi v56, v32 offset:64
	v_bfe_u32 v33, v40, 16, 1
	v_add3_u32 v32, v40, v33, s79
	ds_write_b16_d16_hi v57, v32 offset:64
	v_bfe_u32 v33, v41, 16, 1
	v_add3_u32 v32, v41, v33, s79
	ds_write_b16_d16_hi v58, v32 offset:64
	v_bfe_u32 v33, v42, 16, 1
	v_add3_u32 v32, v42, v33, s79
	ds_write_b16_d16_hi v59, v32 offset:64
	v_bfe_u32 v33, v43, 16, 1
	v_add3_u32 v32, v43, v33, s79
	ds_write_b16_d16_hi v60, v32 offset:64
	v_bfe_u32 v33, v44, 16, 1
	v_add3_u32 v32, v44, v33, s79
	ds_write_b16_d16_hi v61, v32 offset:64
	v_bfe_u32 v33, v45, 16, 1
	v_add3_u32 v32, v45, v33, s79
	ds_write_b16_d16_hi v62, v32 offset:64
	v_bfe_u32 v33, v46, 16, 1
	v_add3_u32 v32, v46, v33, s79
	ds_write_b16_d16_hi v55, v32 offset:64
	v_mov_b32_e32 v32, v47
	s_branch .LBB0_1051

; __device__ __forceinline__ float sigmf(float x) { return 1.f / (1.f + __expf(-x)); }
; template <int MT, int NT, class F>
; __device__ __forceinline__ void acc_foreach(int tid, f32x16 (&acc)[MT][NT], F f) {
;     ...
; #pragma unroll
;   for (int mt = 0; mt < MT; mt++)
; #pragma unroll
;     for (int nt = 0; nt < NT; nt++)
; #pragma unroll
;       for (int i = 0; i < 16; i++) {
;         int row = wm * (MT * 32) + mt * 32 + (i & 3) + 8 * (i >> 2) + 4 * hi;
;         int col = wn * (NT * 32) + nt * 32 + c;
;         f(row, col, acc[mt][nt][i]);
;         if (i == 15) __builtin_amdgcn_sched_barrier(0);
;       }
; __device__ __forceinline__ void inproj_epilogue(const Params& p, int layer, int mt, int ntile, int tid,
;                                                 f32x16 (&acc)[2][2], unsigned char* smem) {
;     ...
;     acc_foreach(tid, acc, [&](int row, int col, float v) {
;       int t = m0 + row;
;       float o = v;
;       if (mode == 1) o = (t >= NPADR) ? v : 0.f;
;       if (mode == 2) o = sigmf(v);
;       sT[row * 136 + col] = f2bf(o);
;     });
.Lfp_3:
	v_bfe_u32 v110, v16, 16, 1
	v_and_b32_e32 v106, 0x5f, v106
	v_add3_u32 v111, v16, v110, s78
	v_mul_lo_u32 v110, v96, s79
	v_lshl_add_u32 v107, v106, 1, v110
	ds_write_b16_d16_hi v107, v111
	v_bfe_u32 v112, v17, 16, 1
	v_add3_u32 v112, v17, v112, s78
	v_add_u32_e32 v111, 0x110, v110
	v_lshl_add_u32 v110, v106, 1, v111
	ds_write_b16_d16_hi v110, v112
	v_bfe_u32 v113, v18, 16, 1
	v_add3_u32 v113, v18, v113, s78
	v_add_u32_e32 v112, 0x110, v111
	v_lshl_add_u32 v111, v106, 1, v112
	ds_write_b16_d16_hi v111, v113
	v_bfe_u32 v114, v19, 16, 1
	v_add3_u32 v114, v19, v114, s78
	v_add_u32_e32 v113, 0x110, v112
	v_lshl_add_u32 v112, v106, 1, v113
	ds_write_b16_d16_hi v112, v114
	v_bfe_u32 v115, v20, 16, 1
	v_add3_u32 v115, v20, v115, s78
	v_add_u32_e32 v114, 0x550, v113
	v_lshl_add_u32 v113, v106, 1, v114
	ds_write_b16_d16_hi v113, v115
	v_bfe_u32 v116, v21, 16, 1
	v_add3_u32 v116, v21, v116, s78
	v_add_u32_e32 v115, 0x110, v114
	v_lshl_add_u32 v114, v106, 1, v115
	ds_write_b16_d16_hi v114, v116
	v_bfe_u32 v117, v22, 16, 1
	v_add3_u32 v117, v22, v117, s78
	v_add_u32_e32 v116, 0x110, v115
	v_lshl_add_u32 v115, v106, 1, v116
	ds_write_b16_d16_hi v115, v117
	v_bfe_u32 v118, v23, 16, 1
	v_add_u32_e32 v116, 0x110, v116
	v_add3_u32 v118, v23, v118, s78
	v_lshl_add_u32 v117, v106, 1, v116
	ds_write_b16_d16_hi v117, v118
	v_bfe_u32 v119, v24, 16, 1
	v_add_u32_e32 v116, 0x550, v116
	v_add3_u32 v119, v24, v119, s78
	v_lshl_add_u32 v118, v106, 1, v116
	ds_write_b16_d16_hi v118, v119
	v_bfe_u32 v120, v25, 16, 1
	v_add_u32_e32 v116, 0x110, v116
	v_add3_u32 v120, v25, v120, s78
	v_lshl_add_u32 v119, v106, 1, v116
	ds_write_b16_d16_hi v119, v120
	v_bfe_u32 v121, v26, 16, 1
	v_add_u32_e32 v116, 0x110, v116
	v_add3_u32 v121, v26, v121, s78
	v_lshl_add_u32 v120, v106, 1, v116
	ds_write_b16_d16_hi v120, v121
	v_bfe_u32 v122, v27, 16, 1
	v_add_u32_e32 v116, 0x110, v116
	v_add3_u32 v122, v27, v122, s78
	v_lshl_add_u32 v121, v106, 1, v116
	ds_write_b16_d16_hi v121, v122
	v_bfe_u32 v123, v28, 16, 1
	v_add_u32_e32 v116, 0x550, v116
	v_add3_u32 v123, v28, v123, s78
	v_lshl_add_u32 v122, v106, 1, v116
	ds_write_b16_d16_hi v122, v123
	v_bfe_u32 v124, v29, 16, 1
	v_add_u32_e32 v116, 0x110, v116
	v_add3_u32 v124, v29, v124, s78
	v_lshl_add_u32 v123, v106, 1, v116
	ds_write_b16_d16_hi v123, v124
	v_bfe_u32 v125, v30, 16, 1
	v_add_u32_e32 v116, 0x110, v116
	v_add3_u32 v124, v30, v125, s78
	v_lshl_add_u32 v116, v106, 1, v116
	ds_write_b16_d16_hi v116, v124
	v_bfe_u32 v125, v31, 16, 1
	v_add3_u32 v124, v31, v125, s78
	ds_write_b16_d16_hi v116, v124 offset:272
	v_bfe_u32 v124, v48, 16, 1
	v_add3_u32 v48, v48, v124, s78
	ds_write_b16_d16_hi v107, v48 offset:64
	v_bfe_u32 v48, v49, 16, 1
	v_add3_u32 v48, v49, v48, s78
	ds_write_b16_d16_hi v110, v48 offset:64
	v_bfe_u32 v49, v50, 16, 1
	v_add3_u32 v48, v50, v49, s78
	ds_write_b16_d16_hi v111, v48 offset:64
	v_bfe_u32 v49, v51, 16, 1
	v_add3_u32 v48, v51, v49, s78
	ds_write_b16_d16_hi v112, v48 offset:64
	v_bfe_u32 v49, v52, 16, 1
	v_add3_u32 v48, v52, v49, s78
	ds_write_b16_d16_hi v113, v48 offset:64
	v_bfe_u32 v49, v53, 16, 1
	v_add3_u32 v48, v53, v49, s78
	ds_write_b16_d16_hi v114, v48 offset:64
	v_bfe_u32 v49, v54, 16, 1
	v_add3_u32 v48, v54, v49, s78
	ds_write_b16_d16_hi v115, v48 offset:64
	v_bfe_u32 v49, v55, 16, 1
	v_add3_u32 v48, v55, v49, s78
	ds_write_b16_d16_hi v117, v48 offset:64
	v_bfe_u32 v49, v56, 16, 1
	v_add3_u32 v48, v56, v49, s78
	ds_write_b16_d16_hi v118, v48 offset:64
	v_bfe_u32 v49, v57, 16, 1
	v_add3_u32 v48, v57, v49, s78
	ds_write_b16_d16_hi v119, v48 offset:64
	v_bfe_u32 v49, v58, 16, 1
	v_add3_u32 v48, v58, v49, s78
	ds_write_b16_d16_hi v120, v48 offset:64
	v_bfe_u32 v49, v59, 16, 1
	v_add3_u32 v48, v59, v49, s78
	ds_write_b16_d16_hi v121, v48 offset:64
	v_bfe_u32 v49, v60, 16, 1
	v_add3_u32 v48, v60, v49, s78
	ds_write_b16_d16_hi v122, v48 offset:64
	v_bfe_u32 v49, v61, 16, 1
	v_add3_u32 v48, v61, v49, s78
	ds_write_b16_d16_hi v123, v48 offset:64
	v_bfe_u32 v49, v62, 16, 1
	v_add3_u32 v48, v62, v49, s78
	ds_write_b16_d16_hi v116, v48 offset:64
	v_bfe_u32 v50, v63, 16, 1
; __device__ __forceinline__ float sigmf(float x) { return 1.f / (1.f + __expf(-x)); }
; template <int MT, int NT, class F>
; __device__ __forceinline__ void acc_foreach(int tid, f32x16 (&acc)[MT][NT], F f) {
;     ...
; #pragma unroll
;   for (int mt = 0; mt < MT; mt++)
; #pragma unroll
;     for (int nt = 0; nt < NT; nt++)
; #pragma unroll
;       for (int i = 0; i < 16; i++) {
;         int row = wm * (MT * 32) + mt * 32 + (i & 3) + 8 * (i >> 2) + 4 * hi;
;         int col = wn * (NT * 32) + nt * 32 + c;
;         f(row, col, acc[mt][nt][i]);
;         if (i == 15) __builtin_amdgcn_sched_barrier(0);
;       }
; __device__ __forceinline__ void inproj_epilogue(const Params& p, int layer, int mt, int ntile, int tid,
;                                                 f32x16 (&acc)[2][2], unsigned char* smem) {
;     ...
;     acc_foreach(tid, acc, [&](int row, int col, float v) {
;       int t = m0 + row;
;       float o = v;
;       if (mode == 1) o = (t >= NPADR) ? v : 0.f;
;       if (mode == 2) o = sigmf(v);
;       sT[row * 136 + col] = f2bf(o);
;     });
	v_add_u32_e32 v49, 0x110, v116
	v_add3_u32 v48, v63, v50, s78
	ds_write_b16_d16_hi v49, v48 offset:64
	v_or_b32_e32 v48, 32, v96
	v_add_u32_e32 v49, s96, v48
	v_cmp_lt_i32_e64 s[8:9], s76, v49
	v_bfe_u32 v50, v0, 16, 1
	v_add3_u32 v50, v0, v50, s78
	v_mul_lo_u32 v49, v48, s79
	v_lshl_add_u32 v48, v106, 1, v49
	ds_write_b16_d16_hi v48, v50
	v_bfe_u32 v51, v1, 16, 1
	v_add3_u32 v51, v1, v51, s78
	v_add_u32_e32 v50, 0x110, v49
	v_lshl_add_u32 v49, v106, 1, v50
	ds_write_b16_d16_hi v49, v51
	v_bfe_u32 v52, v2, 16, 1
	v_add3_u32 v52, v2, v52, s78
	v_add_u32_e32 v51, 0x110, v50
	v_lshl_add_u32 v50, v106, 1, v51
	ds_write_b16_d16_hi v50, v52
	v_bfe_u32 v53, v3, 16, 1
	v_add3_u32 v53, v3, v53, s78
	v_add_u32_e32 v52, 0x110, v51
	v_lshl_add_u32 v51, v106, 1, v52
	ds_write_b16_d16_hi v51, v53
	v_bfe_u32 v54, v4, 16, 1
	v_add3_u32 v54, v4, v54, s78
	v_add_u32_e32 v53, 0x550, v52
	v_lshl_add_u32 v52, v106, 1, v53
	ds_write_b16_d16_hi v52, v54
	v_bfe_u32 v55, v5, 16, 1
	v_add3_u32 v55, v5, v55, s78
	v_add_u32_e32 v54, 0x110, v53
	v_lshl_add_u32 v53, v106, 1, v54
	ds_write_b16_d16_hi v53, v55
	v_bfe_u32 v56, v6, 16, 1
	v_add3_u32 v56, v6, v56, s78
	v_add_u32_e32 v55, 0x110, v54
	v_lshl_add_u32 v54, v106, 1, v55
	ds_write_b16_d16_hi v54, v56
	v_bfe_u32 v57, v7, 16, 1
	v_add_u32_e32 v55, 0x110, v55
	v_add3_u32 v57, v7, v57, s78
	v_lshl_add_u32 v56, v106, 1, v55
	ds_write_b16_d16_hi v56, v57
	v_bfe_u32 v58, v8, 16, 1
	v_add_u32_e32 v55, 0x550, v55
	v_add3_u32 v58, v8, v58, s78
	v_lshl_add_u32 v57, v106, 1, v55
	ds_write_b16_d16_hi v57, v58
	v_bfe_u32 v59, v9, 16, 1
	v_add_u32_e32 v55, 0x110, v55
	v_add3_u32 v59, v9, v59, s78
	v_lshl_add_u32 v58, v106, 1, v55
	ds_write_b16_d16_hi v58, v59
	v_bfe_u32 v60, v10, 16, 1
	v_add_u32_e32 v55, 0x110, v55
	v_add3_u32 v60, v10, v60, s78
	v_lshl_add_u32 v59, v106, 1, v55
	ds_write_b16_d16_hi v59, v60
	v_bfe_u32 v61, v11, 16, 1
	v_add_u32_e32 v55, 0x110, v55
	v_add3_u32 v61, v11, v61, s78
	v_lshl_add_u32 v60, v106, 1, v55
	ds_write_b16_d16_hi v60, v61
	v_bfe_u32 v62, v12, 16, 1
	v_add_u32_e32 v55, 0x550, v55
	v_add3_u32 v62, v12, v62, s78
	v_lshl_add_u32 v61, v106, 1, v55
	ds_write_b16_d16_hi v61, v62
	v_bfe_u32 v63, v13, 16, 1
	v_add_u32_e32 v55, 0x110, v55
	v_add3_u32 v63, v13, v63, s78
	v_lshl_add_u32 v62, v106, 1, v55
	ds_write_b16_d16_hi v62, v63
	v_bfe_u32 v107, v14, 16, 1
	v_add_u32_e32 v55, 0x110, v55
	v_add3_u32 v63, v14, v107, s78
	v_lshl_add_u32 v55, v106, 1, v55
	ds_write_b16_d16_hi v55, v63
	v_bfe_u32 v96, v15, 16, 1
	v_add3_u32 v63, v15, v96, s78
	ds_write_b16_d16_hi v55, v63 offset:272
	v_bfe_u32 v63, v32, 16, 1
	v_add3_u32 v32, v32, v63, s78
	ds_write_b16_d16_hi v48, v32 offset:64
	v_bfe_u32 v32, v33, 16, 1
	v_add3_u32 v32, v33, v32, s78
	ds_write_b16_d16_hi v49, v32 offset:64
	v_bfe_u32 v33, v34, 16, 1
	v_add3_u32 v32, v34, v33, s78
	ds_write_b16_d16_hi v50, v32 offset:64
	v_bfe_u32 v33, v35, 16, 1
	v_add3_u32 v32, v35, v33, s78
	ds_write_b16_d16_hi v51, v32 offset:64
	v_bfe_u32 v33, v36, 16, 1
	v_add3_u32 v32, v36, v33, s78
	ds_write_b16_d16_hi v52, v32 offset:64
	v_bfe_u32 v33, v37, 16, 1
	v_add3_u32 v32, v37, v33, s78
	ds_write_b16_d16_hi v53, v32 offset:64
	v_bfe_u32 v33, v38, 16, 1
	v_add3_u32 v32, v38, v33, s78
	ds_write_b16_d16_hi v54, v32 offset:64
	v_bfe_u32 v33, v39, 16, 1
	v_add3_u32 v32, v39, v33, s78
	ds_write_b16_d16_hi v56, v32 offset:64
	v_bfe_u32 v33, v40, 16, 1
	v_add3_u32 v32, v40, v33, s78
	ds_write_b16_d16_hi v57, v32 offset:64
	v_bfe_u32 v33, v41, 16, 1
	v_add3_u32 v32, v41, v33, s78
	ds_write_b16_d16_hi v58, v32 offset:64
	v_bfe_u32 v33, v42, 16, 1
	v_add3_u32 v32, v42, v33, s78
	ds_write_b16_d16_hi v59, v32 offset:64
	v_bfe_u32 v33, v43, 16, 1
	v_add3_u32 v32, v43, v33, s78
	ds_write_b16_d16_hi v60, v32 offset:64
	v_bfe_u32 v33, v44, 16, 1
	v_add3_u32 v32, v44, v33, s78
	ds_write_b16_d16_hi v61, v32 offset:64
	v_bfe_u32 v33, v45, 16, 1
	v_add3_u32 v32, v45, v33, s78
	ds_write_b16_d16_hi v62, v32 offset:64
	v_bfe_u32 v33, v46, 16, 1
	v_add3_u32 v32, v46, v33, s78
	ds_write_b16_d16_hi v55, v32 offset:64
	v_mov_b32_e32 v32, v47
	s_branch .LBB0_1835

; __device__ __forceinline__ float sigmf(float x) { return 1.f / (1.f + __expf(-x)); }
; template <int MT, int NT, class F>
; __device__ __forceinline__ void acc_foreach(int tid, f32x16 (&acc)[MT][NT], F f) {
;     ...
; #pragma unroll
;   for (int mt = 0; mt < MT; mt++)
; #pragma unroll
;     for (int nt = 0; nt < NT; nt++)
; #pragma unroll
;       for (int i = 0; i < 16; i++) {
;         int row = wm * (MT * 32) + mt * 32 + (i & 3) + 8 * (i >> 2) + 4 * hi;
;         int col = wn * (NT * 32) + nt * 32 + c;
;         f(row, col, acc[mt][nt][i]);
;         if (i == 15) __builtin_amdgcn_sched_barrier(0);
;       }
; __device__ __forceinline__ void inproj_epilogue(const Params& p, int layer, int mt, int ntile, int tid,
;                                                 f32x16 (&acc)[2][2], unsigned char* smem) {
;     ...
;     acc_foreach(tid, acc, [&](int row, int col, float v) {
;       int t = m0 + row;
;       float o = v;
;       if (mode == 1) o = (t >= NPADR) ? v : 0.f;
;       if (mode == 2) o = sigmf(v);
;       sT[row * 136 + col] = f2bf(o);
;     });
.Lfp_4:
	v_bfe_u32 v110, v16, 16, 1
	v_and_b32_e32 v106, 0x5f, v106
	v_add3_u32 v111, v16, v110, s78
	v_mul_lo_u32 v110, v96, s79
	v_lshl_add_u32 v107, v106, 1, v110
	ds_write_b16_d16_hi v107, v111
	v_bfe_u32 v112, v17, 16, 1
	v_add3_u32 v112, v17, v112, s78
	v_add_u32_e32 v111, 0x110, v110
	v_lshl_add_u32 v110, v106, 1, v111
	ds_write_b16_d16_hi v110, v112
	v_bfe_u32 v113, v18, 16, 1
	v_add3_u32 v113, v18, v113, s78
	v_add_u32_e32 v112, 0x110, v111
	v_lshl_add_u32 v111, v106, 1, v112
	ds_write_b16_d16_hi v111, v113
	v_bfe_u32 v114, v19, 16, 1
	v_add3_u32 v114, v19, v114, s78
	v_add_u32_e32 v113, 0x110, v112
	v_lshl_add_u32 v112, v106, 1, v113
	ds_write_b16_d16_hi v112, v114
	v_bfe_u32 v115, v20, 16, 1
	v_add3_u32 v115, v20, v115, s78
	v_add_u32_e32 v114, 0x550, v113
	v_lshl_add_u32 v113, v106, 1, v114
	ds_write_b16_d16_hi v113, v115
	v_bfe_u32 v116, v21, 16, 1
	v_add3_u32 v116, v21, v116, s78
	v_add_u32_e32 v115, 0x110, v114
	v_lshl_add_u32 v114, v106, 1, v115
	ds_write_b16_d16_hi v114, v116
	v_bfe_u32 v117, v22, 16, 1
	v_add3_u32 v117, v22, v117, s78
	v_add_u32_e32 v116, 0x110, v115
	v_lshl_add_u32 v115, v106, 1, v116
	ds_write_b16_d16_hi v115, v117
	v_bfe_u32 v118, v23, 16, 1
	v_add_u32_e32 v116, 0x110, v116
	v_add3_u32 v118, v23, v118, s78
	v_lshl_add_u32 v117, v106, 1, v116
	ds_write_b16_d16_hi v117, v118
	v_bfe_u32 v119, v24, 16, 1
	v_add_u32_e32 v116, 0x550, v116
	v_add3_u32 v119, v24, v119, s78
	v_lshl_add_u32 v118, v106, 1, v116
	ds_write_b16_d16_hi v118, v119
	v_bfe_u32 v120, v25, 16, 1
	v_add_u32_e32 v116, 0x110, v116
	v_add3_u32 v120, v25, v120, s78
	v_lshl_add_u32 v119, v106, 1, v116
	ds_write_b16_d16_hi v119, v120
	v_bfe_u32 v121, v26, 16, 1
	v_add_u32_e32 v116, 0x110, v116
	v_add3_u32 v121, v26, v121, s78
	v_lshl_add_u32 v120, v106, 1, v116
	ds_write_b16_d16_hi v120, v121
	v_bfe_u32 v122, v27, 16, 1
	v_add_u32_e32 v116, 0x110, v116
	v_add3_u32 v122, v27, v122, s78
	v_lshl_add_u32 v121, v106, 1, v116
	ds_write_b16_d16_hi v121, v122
	v_bfe_u32 v123, v28, 16, 1
	v_add_u32_e32 v116, 0x550, v116
	v_add3_u32 v123, v28, v123, s78
	v_lshl_add_u32 v122, v106, 1, v116
	ds_write_b16_d16_hi v122, v123
	v_bfe_u32 v124, v29, 16, 1
	v_add_u32_e32 v116, 0x110, v116
	v_add3_u32 v124, v29, v124, s78
	v_lshl_add_u32 v123, v106, 1, v116
	ds_write_b16_d16_hi v123, v124
	v_bfe_u32 v125, v30, 16, 1
	v_add_u32_e32 v116, 0x110, v116
	v_add3_u32 v124, v30, v125, s78
	v_lshl_add_u32 v116, v106, 1, v116
	ds_write_b16_d16_hi v116, v124
	v_bfe_u32 v125, v31, 16, 1
	v_add3_u32 v124, v31, v125, s78
	ds_write_b16_d16_hi v116, v124 offset:272
	v_bfe_u32 v124, v48, 16, 1
	v_add3_u32 v48, v48, v124, s78
	ds_write_b16_d16_hi v107, v48 offset:64
	v_bfe_u32 v48, v49, 16, 1
	v_add3_u32 v48, v49, v48, s78
	ds_write_b16_d16_hi v110, v48 offset:64
	v_bfe_u32 v49, v50, 16, 1
	v_add3_u32 v48, v50, v49, s78
	ds_write_b16_d16_hi v111, v48 offset:64
	v_bfe_u32 v49, v51, 16, 1
	v_add3_u32 v48, v51, v49, s78
	ds_write_b16_d16_hi v112, v48 offset:64
	v_bfe_u32 v49, v52, 16, 1
	v_add3_u32 v48, v52, v49, s78
	ds_write_b16_d16_hi v113, v48 offset:64
	v_bfe_u32 v49, v53, 16, 1
	v_add3_u32 v48, v53, v49, s78
	ds_write_b16_d16_hi v114, v48 offset:64
	v_bfe_u32 v49, v54, 16, 1
	v_add3_u32 v48, v54, v49, s78
	ds_write_b16_d16_hi v115, v48 offset:64
	v_bfe_u32 v49, v55, 16, 1
	v_add3_u32 v48, v55, v49, s78
	ds_write_b16_d16_hi v117, v48 offset:64
	v_bfe_u32 v49, v56, 16, 1
	v_add3_u32 v48, v56, v49, s78
	ds_write_b16_d16_hi v118, v48 offset:64
	v_bfe_u32 v49, v57, 16, 1
	v_add3_u32 v48, v57, v49, s78
	ds_write_b16_d16_hi v119, v48 offset:64
	v_bfe_u32 v49, v58, 16, 1
	v_add3_u32 v48, v58, v49, s78
	ds_write_b16_d16_hi v120, v48 offset:64
	v_bfe_u32 v49, v59, 16, 1
	v_add3_u32 v48, v59, v49, s78
	ds_write_b16_d16_hi v121, v48 offset:64
	v_bfe_u32 v49, v60, 16, 1
	v_add3_u32 v48, v60, v49, s78
	ds_write_b16_d16_hi v122, v48 offset:64
	v_bfe_u32 v49, v61, 16, 1
	v_add3_u32 v48, v61, v49, s78
	ds_write_b16_d16_hi v123, v48 offset:64
	v_bfe_u32 v49, v62, 16, 1
	v_add3_u32 v48, v62, v49, s78
	ds_write_b16_d16_hi v116, v48 offset:64
	v_bfe_u32 v50, v63, 16, 1
; __device__ __forceinline__ float sigmf(float x) { return 1.f / (1.f + __expf(-x)); }
; template <int MT, int NT, class F>
; __device__ __forceinline__ void acc_foreach(int tid, f32x16 (&acc)[MT][NT], F f) {
;     ...
; #pragma unroll
;   for (int mt = 0; mt < MT; mt++)
; #pragma unroll
;     for (int nt = 0; nt < NT; nt++)
; #pragma unroll
;       for (int i = 0; i < 16; i++) {
;         int row = wm * (MT * 32) + mt * 32 + (i & 3) + 8 * (i >> 2) + 4 * hi;
;         int col = wn * (NT * 32) + nt * 32 + c;
;         f(row, col, acc[mt][nt][i]);
;         if (i == 15) __builtin_amdgcn_sched_barrier(0);
;       }
; __device__ __forceinline__ void inproj_epilogue(const Params& p, int layer, int mt, int ntile, int tid,
;                                                 f32x16 (&acc)[2][2], unsigned char* smem) {
;     ...
;     acc_foreach(tid, acc, [&](int row, int col, float v) {
;       int t = m0 + row;
;       float o = v;
;       if (mode == 1) o = (t >= NPADR) ? v : 0.f;
;       if (mode == 2) o = sigmf(v);
;       sT[row * 136 + col] = f2bf(o);
;     });
	v_add_u32_e32 v49, 0x110, v116
	v_add3_u32 v48, v63, v50, s78
	ds_write_b16_d16_hi v49, v48 offset:64
	v_or_b32_e32 v48, 32, v96
	v_add_u32_e32 v49, s84, v48
	v_cmp_lt_i32_e64 s[8:9], s76, v49
	v_bfe_u32 v50, v0, 16, 1
	v_add3_u32 v50, v0, v50, s78
	v_mul_lo_u32 v49, v48, s79
	v_lshl_add_u32 v48, v106, 1, v49
	ds_write_b16_d16_hi v48, v50
	v_bfe_u32 v51, v1, 16, 1
	v_add3_u32 v51, v1, v51, s78
	v_add_u32_e32 v50, 0x110, v49
	v_lshl_add_u32 v49, v106, 1, v50
	ds_write_b16_d16_hi v49, v51
	v_bfe_u32 v52, v2, 16, 1
	v_add3_u32 v52, v2, v52, s78
	v_add_u32_e32 v51, 0x110, v50
	v_lshl_add_u32 v50, v106, 1, v51
	ds_write_b16_d16_hi v50, v52
	v_bfe_u32 v53, v3, 16, 1
	v_add3_u32 v53, v3, v53, s78
	v_add_u32_e32 v52, 0x110, v51
	v_lshl_add_u32 v51, v106, 1, v52
	ds_write_b16_d16_hi v51, v53
	v_bfe_u32 v54, v4, 16, 1
	v_add3_u32 v54, v4, v54, s78
	v_add_u32_e32 v53, 0x550, v52
	v_lshl_add_u32 v52, v106, 1, v53
	ds_write_b16_d16_hi v52, v54
	v_bfe_u32 v55, v5, 16, 1
	v_add3_u32 v55, v5, v55, s78
	v_add_u32_e32 v54, 0x110, v53
	v_lshl_add_u32 v53, v106, 1, v54
	ds_write_b16_d16_hi v53, v55
	v_bfe_u32 v56, v6, 16, 1
	v_add3_u32 v56, v6, v56, s78
	v_add_u32_e32 v55, 0x110, v54
	v_lshl_add_u32 v54, v106, 1, v55
	ds_write_b16_d16_hi v54, v56
	v_bfe_u32 v57, v7, 16, 1
	v_add_u32_e32 v55, 0x110, v55
	v_add3_u32 v57, v7, v57, s78
	v_lshl_add_u32 v56, v106, 1, v55
	ds_write_b16_d16_hi v56, v57
	v_bfe_u32 v58, v8, 16, 1
	v_add_u32_e32 v55, 0x550, v55
	v_add3_u32 v58, v8, v58, s78
	v_lshl_add_u32 v57, v106, 1, v55
	ds_write_b16_d16_hi v57, v58
	v_bfe_u32 v59, v9, 16, 1
	v_add_u32_e32 v55, 0x110, v55
	v_add3_u32 v59, v9, v59, s78
	v_lshl_add_u32 v58, v106, 1, v55
	ds_write_b16_d16_hi v58, v59
	v_bfe_u32 v60, v10, 16, 1
	v_add_u32_e32 v55, 0x110, v55
	v_add3_u32 v60, v10, v60, s78
	v_lshl_add_u32 v59, v106, 1, v55
	ds_write_b16_d16_hi v59, v60
	v_bfe_u32 v61, v11, 16, 1
	v_add_u32_e32 v55, 0x110, v55
	v_add3_u32 v61, v11, v61, s78
	v_lshl_add_u32 v60, v106, 1, v55
	ds_write_b16_d16_hi v60, v61
	v_bfe_u32 v62, v12, 16, 1
	v_add_u32_e32 v55, 0x550, v55
	v_add3_u32 v62, v12, v62, s78
	v_lshl_add_u32 v61, v106, 1, v55
	ds_write_b16_d16_hi v61, v62
	v_bfe_u32 v63, v13, 16, 1
	v_add_u32_e32 v55, 0x110, v55
	v_add3_u32 v63, v13, v63, s78
	v_lshl_add_u32 v62, v106, 1, v55
	ds_write_b16_d16_hi v62, v63
	v_bfe_u32 v107, v14, 16, 1
	v_add_u32_e32 v55, 0x110, v55
	v_add3_u32 v63, v14, v107, s78
	v_lshl_add_u32 v55, v106, 1, v55
	ds_write_b16_d16_hi v55, v63
	v_bfe_u32 v96, v15, 16, 1
	v_add3_u32 v63, v15, v96, s78
	ds_write_b16_d16_hi v55, v63 offset:272
	v_bfe_u32 v63, v32, 16, 1
	v_add3_u32 v32, v32, v63, s78
	ds_write_b16_d16_hi v48, v32 offset:64
	v_bfe_u32 v32, v33, 16, 1
	v_add3_u32 v32, v33, v32, s78
	ds_write_b16_d16_hi v49, v32 offset:64
	v_bfe_u32 v33, v34, 16, 1
	v_add3_u32 v32, v34, v33, s78
	ds_write_b16_d16_hi v50, v32 offset:64
	v_bfe_u32 v33, v35, 16, 1
	v_add3_u32 v32, v35, v33, s78
	ds_write_b16_d16_hi v51, v32 offset:64
	v_bfe_u32 v33, v36, 16, 1
	v_add3_u32 v32, v36, v33, s78
	ds_write_b16_d16_hi v52, v32 offset:64
	v_bfe_u32 v33, v37, 16, 1
	v_add3_u32 v32, v37, v33, s78
	ds_write_b16_d16_hi v53, v32 offset:64
	v_bfe_u32 v33, v38, 16, 1
	v_add3_u32 v32, v38, v33, s78
	ds_write_b16_d16_hi v54, v32 offset:64
	v_bfe_u32 v33, v39, 16, 1
	v_add3_u32 v32, v39, v33, s78
	ds_write_b16_d16_hi v56, v32 offset:64
	v_bfe_u32 v33, v40, 16, 1
	v_add3_u32 v32, v40, v33, s78
	ds_write_b16_d16_hi v57, v32 offset:64
	v_bfe_u32 v33, v41, 16, 1
	v_add3_u32 v32, v41, v33, s78
	ds_write_b16_d16_hi v58, v32 offset:64
	v_bfe_u32 v33, v42, 16, 1
	v_add3_u32 v32, v42, v33, s78
	ds_write_b16_d16_hi v59, v32 offset:64
	v_bfe_u32 v33, v43, 16, 1
	v_add3_u32 v32, v43, v33, s78
	ds_write_b16_d16_hi v60, v32 offset:64
	v_bfe_u32 v33, v44, 16, 1
	v_add3_u32 v32, v44, v33, s78
	ds_write_b16_d16_hi v61, v32 offset:64
	v_bfe_u32 v33, v45, 16, 1
	v_add3_u32 v32, v45, v33, s78
	ds_write_b16_d16_hi v62, v32 offset:64
	v_bfe_u32 v33, v46, 16, 1
	v_add3_u32 v32, v46, v33, s78
	ds_write_b16_d16_hi v55, v32 offset:64
	v_mov_b32_e32 v32, v47
	s_branch .LBB0_2226

; __device__ __forceinline__ float sigmf(float x) { return 1.f / (1.f + __expf(-x)); }
; template <int MT, int NT, class F>
; __device__ __forceinline__ void acc_foreach(int tid, f32x16 (&acc)[MT][NT], F f) {
;     ...
; #pragma unroll
;   for (int mt = 0; mt < MT; mt++)
; #pragma unroll
;     for (int nt = 0; nt < NT; nt++)
; #pragma unroll
;       for (int i = 0; i < 16; i++) {
;         int row = wm * (MT * 32) + mt * 32 + (i & 3) + 8 * (i >> 2) + 4 * hi;
;         int col = wn * (NT * 32) + nt * 32 + c;
;         f(row, col, acc[mt][nt][i]);
;         if (i == 15) __builtin_amdgcn_sched_barrier(0);
;       }
; __device__ __forceinline__ void inproj_epilogue(const Params& p, int layer, int mt, int ntile, int tid,
;                                                 f32x16 (&acc)[2][2], unsigned char* smem) {
;     ...
;     acc_foreach(tid, acc, [&](int row, int col, float v) {
;       int t = m0 + row;
;       float o = v;
;       if (mode == 1) o = (t >= NPADR) ? v : 0.f;
;       if (mode == 2) o = sigmf(v);
;       sT[row * 136 + col] = f2bf(o);
;     });
.Lfp_5:
	v_bfe_u32 v110, v16, 16, 1
	v_and_b32_e32 v106, 0x5f, v106
	v_add3_u32 v111, v16, v110, s81
	v_mul_lo_u32 v110, v96, s82
	v_lshl_add_u32 v107, v106, 1, v110
	ds_write_b16_d16_hi v107, v111
	v_add3_u32 v111, s96, v96, 1
	v_cmp_lt_i32_e64 s[10:11], s79, v111
	v_bfe_u32 v112, v17, 16, 1
	v_add3_u32 v112, v17, v112, s81
	v_add_u32_e32 v111, 0x110, v110
	v_lshl_add_u32 v110, v106, 1, v111
	ds_write_b16_d16_hi v110, v112
	v_bfe_u32 v113, v18, 16, 1
	v_add3_u32 v113, v18, v113, s81
	v_add_u32_e32 v112, 0x110, v111
	v_lshl_add_u32 v111, v106, 1, v112
	ds_write_b16_d16_hi v111, v113
	v_bfe_u32 v114, v19, 16, 1
	v_add3_u32 v114, v19, v114, s81
	v_add_u32_e32 v113, 0x110, v112
	v_lshl_add_u32 v112, v106, 1, v113
	ds_write_b16_d16_hi v112, v114
	v_bfe_u32 v115, v20, 16, 1
	v_add3_u32 v115, v20, v115, s81
	v_add_u32_e32 v114, 0x550, v113
	v_lshl_add_u32 v113, v106, 1, v114
	ds_write_b16_d16_hi v113, v115
	v_bfe_u32 v116, v21, 16, 1
	v_add3_u32 v116, v21, v116, s81
	v_add_u32_e32 v115, 0x110, v114
	v_lshl_add_u32 v114, v106, 1, v115
	ds_write_b16_d16_hi v114, v116
	v_bfe_u32 v117, v22, 16, 1
	v_add3_u32 v117, v22, v117, s81
	v_add_u32_e32 v116, 0x110, v115
	v_lshl_add_u32 v115, v106, 1, v116
	ds_write_b16_d16_hi v115, v117
	v_bfe_u32 v118, v23, 16, 1
	v_add_u32_e32 v116, 0x110, v116
	v_add3_u32 v118, v23, v118, s81
	v_lshl_add_u32 v117, v106, 1, v116
	ds_write_b16_d16_hi v117, v118
	v_bfe_u32 v119, v24, 16, 1
	v_add_u32_e32 v116, 0x550, v116
	v_add3_u32 v119, v24, v119, s81
	v_lshl_add_u32 v118, v106, 1, v116
	ds_write_b16_d16_hi v118, v119
	v_bfe_u32 v120, v25, 16, 1
	v_add_u32_e32 v116, 0x110, v116
	v_add3_u32 v120, v25, v120, s81
	v_lshl_add_u32 v119, v106, 1, v116
	ds_write_b16_d16_hi v119, v120
	v_bfe_u32 v121, v26, 16, 1
	v_add_u32_e32 v116, 0x110, v116
	v_add3_u32 v121, v26, v121, s81
	v_lshl_add_u32 v120, v106, 1, v116
	ds_write_b16_d16_hi v120, v121
	v_bfe_u32 v122, v27, 16, 1
	v_add_u32_e32 v116, 0x110, v116
	v_add3_u32 v122, v27, v122, s81
	v_lshl_add_u32 v121, v106, 1, v116
	ds_write_b16_d16_hi v121, v122
	v_bfe_u32 v123, v28, 16, 1
	v_add_u32_e32 v116, 0x550, v116
	v_add3_u32 v123, v28, v123, s81
	v_lshl_add_u32 v122, v106, 1, v116
	ds_write_b16_d16_hi v122, v123
	v_bfe_u32 v124, v29, 16, 1
	v_add_u32_e32 v116, 0x110, v116
	v_add3_u32 v124, v29, v124, s81
	v_lshl_add_u32 v123, v106, 1, v116
	ds_write_b16_d16_hi v123, v124
	v_bfe_u32 v125, v30, 16, 1
	v_add_u32_e32 v116, 0x110, v116
	v_add3_u32 v124, v30, v125, s81
	v_lshl_add_u32 v116, v106, 1, v116
	ds_write_b16_d16_hi v116, v124
	v_bfe_u32 v125, v31, 16, 1
	v_add3_u32 v124, v31, v125, s81
	ds_write_b16_d16_hi v116, v124 offset:272
	v_bfe_u32 v124, v48, 16, 1
	v_add3_u32 v48, v48, v124, s81
	ds_write_b16_d16_hi v107, v48 offset:64
	v_bfe_u32 v48, v49, 16, 1
	v_add3_u32 v48, v49, v48, s81
	ds_write_b16_d16_hi v110, v48 offset:64
	v_bfe_u32 v49, v50, 16, 1
	v_add3_u32 v48, v50, v49, s81
	ds_write_b16_d16_hi v111, v48 offset:64
	v_bfe_u32 v49, v51, 16, 1
	v_add3_u32 v48, v51, v49, s81
	ds_write_b16_d16_hi v112, v48 offset:64
	v_bfe_u32 v49, v52, 16, 1
	v_add3_u32 v48, v52, v49, s81
	ds_write_b16_d16_hi v113, v48 offset:64
	v_bfe_u32 v49, v53, 16, 1
	v_add3_u32 v48, v53, v49, s81
	ds_write_b16_d16_hi v114, v48 offset:64
	v_bfe_u32 v49, v54, 16, 1
	v_add3_u32 v48, v54, v49, s81
	ds_write_b16_d16_hi v115, v48 offset:64
	v_bfe_u32 v49, v55, 16, 1
	v_add3_u32 v48, v55, v49, s81
	ds_write_b16_d16_hi v117, v48 offset:64
	v_bfe_u32 v49, v56, 16, 1
	v_add3_u32 v48, v56, v49, s81
	ds_write_b16_d16_hi v118, v48 offset:64
	v_bfe_u32 v49, v57, 16, 1
	v_add3_u32 v48, v57, v49, s81
	ds_write_b16_d16_hi v119, v48 offset:64
	v_bfe_u32 v49, v58, 16, 1
	v_add3_u32 v48, v58, v49, s81
	ds_write_b16_d16_hi v120, v48 offset:64
	v_bfe_u32 v49, v59, 16, 1
	v_add3_u32 v48, v59, v49, s81
	ds_write_b16_d16_hi v121, v48 offset:64
	v_bfe_u32 v49, v60, 16, 1
	v_add3_u32 v48, v60, v49, s81
	ds_write_b16_d16_hi v122, v48 offset:64
	v_bfe_u32 v49, v61, 16, 1
	v_add3_u32 v48, v61, v49, s81
	ds_write_b16_d16_hi v123, v48 offset:64
	v_bfe_u32 v49, v62, 16, 1
	v_add3_u32 v48, v62, v49, s81
	ds_write_b16_d16_hi v116, v48 offset:64
; __device__ __forceinline__ float sigmf(float x) { return 1.f / (1.f + __expf(-x)); }
; template <int MT, int NT, class F>
; __device__ __forceinline__ void acc_foreach(int tid, f32x16 (&acc)[MT][NT], F f) {
;     ...
; #pragma unroll
;   for (int mt = 0; mt < MT; mt++)
; #pragma unroll
;     for (int nt = 0; nt < NT; nt++)
; #pragma unroll
;       for (int i = 0; i < 16; i++) {
;         int row = wm * (MT * 32) + mt * 32 + (i & 3) + 8 * (i >> 2) + 4 * hi;
;         int col = wn * (NT * 32) + nt * 32 + c;
;         f(row, col, acc[mt][nt][i]);
;         if (i == 15) __builtin_amdgcn_sched_barrier(0);
;       }
; __device__ __forceinline__ void inproj_epilogue(const Params& p, int layer, int mt, int ntile, int tid,
;                                                 f32x16 (&acc)[2][2], unsigned char* smem) {
;     ...
;     acc_foreach(tid, acc, [&](int row, int col, float v) {
;       int t = m0 + row;
;       float o = v;
;       if (mode == 1) o = (t >= NPADR) ? v : 0.f;
;       if (mode == 2) o = sigmf(v);
;       sT[row * 136 + col] = f2bf(o);
;     });
	v_bfe_u32 v50, v63, 16, 1
	v_add_u32_e32 v49, 0x110, v116
	v_add3_u32 v48, v63, v50, s81
	ds_write_b16_d16_hi v49, v48 offset:64
	v_or_b32_e32 v48, 32, v96
	v_add_u32_e32 v49, s96, v48
	v_cmp_lt_i32_e64 s[8:9], s79, v49
	v_bfe_u32 v50, v0, 16, 1
	v_add3_u32 v50, v0, v50, s81
	v_mul_lo_u32 v49, v48, s82
	v_lshl_add_u32 v48, v106, 1, v49
	ds_write_b16_d16_hi v48, v50
	v_bfe_u32 v51, v1, 16, 1
	v_add3_u32 v51, v1, v51, s81
	v_add_u32_e32 v50, 0x110, v49
	v_lshl_add_u32 v49, v106, 1, v50
	ds_write_b16_d16_hi v49, v51
	v_bfe_u32 v52, v2, 16, 1
	v_add3_u32 v52, v2, v52, s81
	v_add_u32_e32 v51, 0x110, v50
	v_lshl_add_u32 v50, v106, 1, v51
	ds_write_b16_d16_hi v50, v52
	v_bfe_u32 v53, v3, 16, 1
	v_add3_u32 v53, v3, v53, s81
	v_add_u32_e32 v52, 0x110, v51
	v_lshl_add_u32 v51, v106, 1, v52
	ds_write_b16_d16_hi v51, v53
	v_bfe_u32 v54, v4, 16, 1
	v_add3_u32 v54, v4, v54, s81
	v_add_u32_e32 v53, 0x550, v52
	v_lshl_add_u32 v52, v106, 1, v53
	ds_write_b16_d16_hi v52, v54
	v_bfe_u32 v55, v5, 16, 1
	v_add3_u32 v55, v5, v55, s81
	v_add_u32_e32 v54, 0x110, v53
	v_lshl_add_u32 v53, v106, 1, v54
	ds_write_b16_d16_hi v53, v55
	v_bfe_u32 v56, v6, 16, 1
	v_add3_u32 v56, v6, v56, s81
	v_add_u32_e32 v55, 0x110, v54
	v_lshl_add_u32 v54, v106, 1, v55
	ds_write_b16_d16_hi v54, v56
	v_bfe_u32 v57, v7, 16, 1
	v_add_u32_e32 v55, 0x110, v55
	v_add3_u32 v57, v7, v57, s81
	v_lshl_add_u32 v56, v106, 1, v55
	ds_write_b16_d16_hi v56, v57
	v_bfe_u32 v58, v8, 16, 1
	v_add_u32_e32 v55, 0x550, v55
	v_add3_u32 v58, v8, v58, s81
	v_lshl_add_u32 v57, v106, 1, v55
	ds_write_b16_d16_hi v57, v58
	v_bfe_u32 v59, v9, 16, 1
	v_add_u32_e32 v55, 0x110, v55
	v_add3_u32 v59, v9, v59, s81
	v_lshl_add_u32 v58, v106, 1, v55
	ds_write_b16_d16_hi v58, v59
	v_bfe_u32 v60, v10, 16, 1
	v_add_u32_e32 v55, 0x110, v55
	v_add3_u32 v60, v10, v60, s81
	v_lshl_add_u32 v59, v106, 1, v55
	ds_write_b16_d16_hi v59, v60
	v_bfe_u32 v61, v11, 16, 1
	v_add_u32_e32 v55, 0x110, v55
	v_add3_u32 v61, v11, v61, s81
	v_lshl_add_u32 v60, v106, 1, v55
	ds_write_b16_d16_hi v60, v61
	v_bfe_u32 v62, v12, 16, 1
	v_add_u32_e32 v55, 0x550, v55
	v_add3_u32 v62, v12, v62, s81
	v_lshl_add_u32 v61, v106, 1, v55
	ds_write_b16_d16_hi v61, v62
	v_bfe_u32 v63, v13, 16, 1
	v_add_u32_e32 v55, 0x110, v55
	v_add3_u32 v63, v13, v63, s81
	v_lshl_add_u32 v62, v106, 1, v55
	ds_write_b16_d16_hi v62, v63
	v_bfe_u32 v107, v14, 16, 1
	v_add_u32_e32 v55, 0x110, v55
	v_add3_u32 v63, v14, v107, s81
	v_lshl_add_u32 v55, v106, 1, v55
	ds_write_b16_d16_hi v55, v63
	v_bfe_u32 v96, v15, 16, 1
	v_add3_u32 v63, v15, v96, s81
	ds_write_b16_d16_hi v55, v63 offset:272
	v_bfe_u32 v63, v32, 16, 1
	v_add3_u32 v32, v32, v63, s81
	ds_write_b16_d16_hi v48, v32 offset:64
	v_bfe_u32 v32, v33, 16, 1
	v_add3_u32 v32, v33, v32, s81
	ds_write_b16_d16_hi v49, v32 offset:64
	v_bfe_u32 v33, v34, 16, 1
	v_add3_u32 v32, v34, v33, s81
	ds_write_b16_d16_hi v50, v32 offset:64
	v_bfe_u32 v33, v35, 16, 1
	v_add3_u32 v32, v35, v33, s81
	ds_write_b16_d16_hi v51, v32 offset:64
	v_bfe_u32 v33, v36, 16, 1
	v_add3_u32 v32, v36, v33, s81
	ds_write_b16_d16_hi v52, v32 offset:64
	v_bfe_u32 v33, v37, 16, 1
	v_add3_u32 v32, v37, v33, s81
	ds_write_b16_d16_hi v53, v32 offset:64
	v_bfe_u32 v33, v38, 16, 1
	v_add3_u32 v32, v38, v33, s81
	ds_write_b16_d16_hi v54, v32 offset:64
	v_bfe_u32 v33, v39, 16, 1
	v_add3_u32 v32, v39, v33, s81
	ds_write_b16_d16_hi v56, v32 offset:64
	v_bfe_u32 v33, v40, 16, 1
	v_add3_u32 v32, v40, v33, s81
	ds_write_b16_d16_hi v57, v32 offset:64
	v_bfe_u32 v33, v41, 16, 1
	v_add3_u32 v32, v41, v33, s81
	ds_write_b16_d16_hi v58, v32 offset:64
	v_bfe_u32 v33, v42, 16, 1
	v_add3_u32 v32, v42, v33, s81
	ds_write_b16_d16_hi v59, v32 offset:64
	v_bfe_u32 v33, v43, 16, 1
	v_add3_u32 v32, v43, v33, s81
	ds_write_b16_d16_hi v60, v32 offset:64
	v_bfe_u32 v33, v44, 16, 1
	v_add3_u32 v32, v44, v33, s81
	ds_write_b16_d16_hi v61, v32 offset:64
	v_bfe_u32 v33, v45, 16, 1
	v_add3_u32 v32, v45, v33, s81
	ds_write_b16_d16_hi v62, v32 offset:64
	v_bfe_u32 v33, v46, 16, 1
	v_add3_u32 v32, v46, v33, s81
	ds_write_b16_d16_hi v55, v32 offset:64
	v_mov_b32_e32 v32, v47
	s_branch .LBB0_2906

; __device__ __forceinline__ float sigmf(float x) { return 1.f / (1.f + __expf(-x)); }
; template <int MT, int NT, class F>
; __device__ __forceinline__ void acc_foreach(int tid, f32x16 (&acc)[MT][NT], F f) {
;     ...
; #pragma unroll
;   for (int mt = 0; mt < MT; mt++)
; #pragma unroll
;     for (int nt = 0; nt < NT; nt++)
; #pragma unroll
;       for (int i = 0; i < 16; i++) {
;         int row = wm * (MT * 32) + mt * 32 + (i & 3) + 8 * (i >> 2) + 4 * hi;
;         int col = wn * (NT * 32) + nt * 32 + c;
;         f(row, col, acc[mt][nt][i]);
;         if (i == 15) __builtin_amdgcn_sched_barrier(0);
;       }
; __device__ __forceinline__ void inproj_epilogue(const Params& p, int layer, int mt, int ntile, int tid,
;                                                 f32x16 (&acc)[2][2], unsigned char* smem) {
;     ...
;     acc_foreach(tid, acc, [&](int row, int col, float v) {
;       int t = m0 + row;
;       float o = v;
;       if (mode == 1) o = (t >= NPADR) ? v : 0.f;
;       if (mode == 2) o = sigmf(v);
;       sT[row * 136 + col] = f2bf(o);
;     });
.Lfp_6:
	v_bfe_u32 v110, v16, 16, 1
	v_and_b32_e32 v106, 0x5f, v106
	v_add3_u32 v111, v16, v110, s79
	v_mul_lo_u32 v110, v96, s80
	v_lshl_add_u32 v107, v106, 1, v110
	ds_write_b16_d16_hi v107, v111
	v_add3_u32 v111, s94, v96, 1
	v_cmp_lt_i32_e64 s[10:11], s77, v111
	v_bfe_u32 v112, v17, 16, 1
	v_add3_u32 v112, v17, v112, s79
	v_add_u32_e32 v111, 0x110, v110
	v_lshl_add_u32 v110, v106, 1, v111
	ds_write_b16_d16_hi v110, v112
	v_bfe_u32 v113, v18, 16, 1
	v_add3_u32 v113, v18, v113, s79
	v_add_u32_e32 v112, 0x110, v111
	v_lshl_add_u32 v111, v106, 1, v112
	ds_write_b16_d16_hi v111, v113
	v_bfe_u32 v114, v19, 16, 1
	v_add3_u32 v114, v19, v114, s79
	v_add_u32_e32 v113, 0x110, v112
	v_lshl_add_u32 v112, v106, 1, v113
	ds_write_b16_d16_hi v112, v114
	v_bfe_u32 v115, v20, 16, 1
	v_add3_u32 v115, v20, v115, s79
	v_add_u32_e32 v114, 0x550, v113
	v_lshl_add_u32 v113, v106, 1, v114
	ds_write_b16_d16_hi v113, v115
	v_bfe_u32 v116, v21, 16, 1
	v_add3_u32 v116, v21, v116, s79
	v_add_u32_e32 v115, 0x110, v114
	v_lshl_add_u32 v114, v106, 1, v115
	ds_write_b16_d16_hi v114, v116
	v_bfe_u32 v117, v22, 16, 1
	v_add3_u32 v117, v22, v117, s79
	v_add_u32_e32 v116, 0x110, v115
	v_lshl_add_u32 v115, v106, 1, v116
	ds_write_b16_d16_hi v115, v117
	v_bfe_u32 v118, v23, 16, 1
	v_add_u32_e32 v116, 0x110, v116
	v_add3_u32 v118, v23, v118, s79
	v_lshl_add_u32 v117, v106, 1, v116
	ds_write_b16_d16_hi v117, v118
	v_bfe_u32 v119, v24, 16, 1
	v_add_u32_e32 v116, 0x550, v116
	v_add3_u32 v119, v24, v119, s79
	v_lshl_add_u32 v118, v106, 1, v116
	ds_write_b16_d16_hi v118, v119
	v_bfe_u32 v120, v25, 16, 1
	v_add_u32_e32 v116, 0x110, v116
	v_add3_u32 v120, v25, v120, s79
	v_lshl_add_u32 v119, v106, 1, v116
	ds_write_b16_d16_hi v119, v120
	v_bfe_u32 v121, v26, 16, 1
	v_add_u32_e32 v116, 0x110, v116
	v_add3_u32 v121, v26, v121, s79
	v_lshl_add_u32 v120, v106, 1, v116
	ds_write_b16_d16_hi v120, v121
	v_bfe_u32 v122, v27, 16, 1
	v_add_u32_e32 v116, 0x110, v116
	v_add3_u32 v122, v27, v122, s79
	v_lshl_add_u32 v121, v106, 1, v116
	ds_write_b16_d16_hi v121, v122
	v_bfe_u32 v123, v28, 16, 1
	v_add_u32_e32 v116, 0x550, v116
	v_add3_u32 v123, v28, v123, s79
	v_lshl_add_u32 v122, v106, 1, v116
	ds_write_b16_d16_hi v122, v123
	v_bfe_u32 v124, v29, 16, 1
	v_add_u32_e32 v116, 0x110, v116
	v_add3_u32 v124, v29, v124, s79
	v_lshl_add_u32 v123, v106, 1, v116
	ds_write_b16_d16_hi v123, v124
	v_bfe_u32 v125, v30, 16, 1
	v_add_u32_e32 v116, 0x110, v116
	v_add3_u32 v124, v30, v125, s79
	v_lshl_add_u32 v116, v106, 1, v116
	ds_write_b16_d16_hi v116, v124
	v_bfe_u32 v125, v31, 16, 1
	v_add3_u32 v124, v31, v125, s79
	ds_write_b16_d16_hi v116, v124 offset:272
	v_bfe_u32 v124, v48, 16, 1
	v_add3_u32 v48, v48, v124, s79
	ds_write_b16_d16_hi v107, v48 offset:64
	v_bfe_u32 v48, v49, 16, 1
	v_add3_u32 v48, v49, v48, s79
	ds_write_b16_d16_hi v110, v48 offset:64
	v_bfe_u32 v49, v50, 16, 1
	v_add3_u32 v48, v50, v49, s79
	ds_write_b16_d16_hi v111, v48 offset:64
	v_bfe_u32 v49, v51, 16, 1
	v_add3_u32 v48, v51, v49, s79
	ds_write_b16_d16_hi v112, v48 offset:64
	v_bfe_u32 v49, v52, 16, 1
	v_add3_u32 v48, v52, v49, s79
	ds_write_b16_d16_hi v113, v48 offset:64
	v_bfe_u32 v49, v53, 16, 1
	v_add3_u32 v48, v53, v49, s79
	ds_write_b16_d16_hi v114, v48 offset:64
	v_bfe_u32 v49, v54, 16, 1
	v_add3_u32 v48, v54, v49, s79
	ds_write_b16_d16_hi v115, v48 offset:64
	v_bfe_u32 v49, v55, 16, 1
	v_add3_u32 v48, v55, v49, s79
	ds_write_b16_d16_hi v117, v48 offset:64
	v_bfe_u32 v49, v56, 16, 1
	v_add3_u32 v48, v56, v49, s79
	ds_write_b16_d16_hi v118, v48 offset:64
	v_bfe_u32 v49, v57, 16, 1
	v_add3_u32 v48, v57, v49, s79
	ds_write_b16_d16_hi v119, v48 offset:64
	v_bfe_u32 v49, v58, 16, 1
	v_add3_u32 v48, v58, v49, s79
	ds_write_b16_d16_hi v120, v48 offset:64
	v_bfe_u32 v49, v59, 16, 1
	v_add3_u32 v48, v59, v49, s79
	ds_write_b16_d16_hi v121, v48 offset:64
	v_bfe_u32 v49, v60, 16, 1
	v_add3_u32 v48, v60, v49, s79
	ds_write_b16_d16_hi v122, v48 offset:64
	v_bfe_u32 v49, v61, 16, 1
	v_add3_u32 v48, v61, v49, s79
	ds_write_b16_d16_hi v123, v48 offset:64
	v_bfe_u32 v49, v62, 16, 1
	v_add3_u32 v48, v62, v49, s79
	ds_write_b16_d16_hi v116, v48 offset:64
; __device__ __forceinline__ float sigmf(float x) { return 1.f / (1.f + __expf(-x)); }
; template <int MT, int NT, class F>
; __device__ __forceinline__ void acc_foreach(int tid, f32x16 (&acc)[MT][NT], F f) {
;     ...
; #pragma unroll
;   for (int mt = 0; mt < MT; mt++)
; #pragma unroll
;     for (int nt = 0; nt < NT; nt++)
; #pragma unroll
;       for (int i = 0; i < 16; i++) {
;         int row = wm * (MT * 32) + mt * 32 + (i & 3) + 8 * (i >> 2) + 4 * hi;
;         int col = wn * (NT * 32) + nt * 32 + c;
;         f(row, col, acc[mt][nt][i]);
;         if (i == 15) __builtin_amdgcn_sched_barrier(0);
;       }
; __device__ __forceinline__ void inproj_epilogue(const Params& p, int layer, int mt, int ntile, int tid,
;                                                 f32x16 (&acc)[2][2], unsigned char* smem) {
;     ...
;     acc_foreach(tid, acc, [&](int row, int col, float v) {
;       int t = m0 + row;
;       float o = v;
;       if (mode == 1) o = (t >= NPADR) ? v : 0.f;
;       if (mode == 2) o = sigmf(v);
;       sT[row * 136 + col] = f2bf(o);
;     });
	v_bfe_u32 v50, v63, 16, 1
	v_add_u32_e32 v49, 0x110, v116
	v_add3_u32 v48, v63, v50, s79
	ds_write_b16_d16_hi v49, v48 offset:64
	v_or_b32_e32 v48, 32, v96
	v_add_u32_e32 v49, s94, v48
	v_cmp_lt_i32_e64 s[8:9], s77, v49
	v_bfe_u32 v50, v0, 16, 1
	v_add3_u32 v50, v0, v50, s79
	v_mul_lo_u32 v49, v48, s80
	v_lshl_add_u32 v48, v106, 1, v49
	ds_write_b16_d16_hi v48, v50
	v_bfe_u32 v51, v1, 16, 1
	v_add3_u32 v51, v1, v51, s79
	v_add_u32_e32 v50, 0x110, v49
	v_lshl_add_u32 v49, v106, 1, v50
	ds_write_b16_d16_hi v49, v51
	v_bfe_u32 v52, v2, 16, 1
	v_add3_u32 v52, v2, v52, s79
	v_add_u32_e32 v51, 0x110, v50
	v_lshl_add_u32 v50, v106, 1, v51
	ds_write_b16_d16_hi v50, v52
	v_bfe_u32 v53, v3, 16, 1
	v_add3_u32 v53, v3, v53, s79
	v_add_u32_e32 v52, 0x110, v51
	v_lshl_add_u32 v51, v106, 1, v52
	ds_write_b16_d16_hi v51, v53
	v_bfe_u32 v54, v4, 16, 1
	v_add3_u32 v54, v4, v54, s79
	v_add_u32_e32 v53, 0x550, v52
	v_lshl_add_u32 v52, v106, 1, v53
	ds_write_b16_d16_hi v52, v54
	v_bfe_u32 v55, v5, 16, 1
	v_add3_u32 v55, v5, v55, s79
	v_add_u32_e32 v54, 0x110, v53
	v_lshl_add_u32 v53, v106, 1, v54
	ds_write_b16_d16_hi v53, v55
	v_bfe_u32 v56, v6, 16, 1
	v_add3_u32 v56, v6, v56, s79
	v_add_u32_e32 v55, 0x110, v54
	v_lshl_add_u32 v54, v106, 1, v55
	ds_write_b16_d16_hi v54, v56
	v_bfe_u32 v57, v7, 16, 1
	v_add_u32_e32 v55, 0x110, v55
	v_add3_u32 v57, v7, v57, s79
	v_lshl_add_u32 v56, v106, 1, v55
	ds_write_b16_d16_hi v56, v57
	v_bfe_u32 v58, v8, 16, 1
	v_add_u32_e32 v55, 0x550, v55
	v_add3_u32 v58, v8, v58, s79
	v_lshl_add_u32 v57, v106, 1, v55
	ds_write_b16_d16_hi v57, v58
	v_bfe_u32 v59, v9, 16, 1
	v_add_u32_e32 v55, 0x110, v55
	v_add3_u32 v59, v9, v59, s79
	v_lshl_add_u32 v58, v106, 1, v55
	ds_write_b16_d16_hi v58, v59
	v_bfe_u32 v60, v10, 16, 1
	v_add_u32_e32 v55, 0x110, v55
	v_add3_u32 v60, v10, v60, s79
	v_lshl_add_u32 v59, v106, 1, v55
	ds_write_b16_d16_hi v59, v60
	v_bfe_u32 v61, v11, 16, 1
	v_add_u32_e32 v55, 0x110, v55
	v_add3_u32 v61, v11, v61, s79
	v_lshl_add_u32 v60, v106, 1, v55
	ds_write_b16_d16_hi v60, v61
	v_bfe_u32 v62, v12, 16, 1
	v_add_u32_e32 v55, 0x550, v55
	v_add3_u32 v62, v12, v62, s79
	v_lshl_add_u32 v61, v106, 1, v55
	ds_write_b16_d16_hi v61, v62
	v_bfe_u32 v63, v13, 16, 1
	v_add_u32_e32 v55, 0x110, v55
	v_add3_u32 v63, v13, v63, s79
	v_lshl_add_u32 v62, v106, 1, v55
	ds_write_b16_d16_hi v62, v63
	v_bfe_u32 v107, v14, 16, 1
	v_add_u32_e32 v55, 0x110, v55
	v_add3_u32 v63, v14, v107, s79
	v_lshl_add_u32 v55, v106, 1, v55
	ds_write_b16_d16_hi v55, v63
	v_bfe_u32 v96, v15, 16, 1
	v_add3_u32 v63, v15, v96, s79
	ds_write_b16_d16_hi v55, v63 offset:272
	v_bfe_u32 v63, v32, 16, 1
	v_add3_u32 v32, v32, v63, s79
	ds_write_b16_d16_hi v48, v32 offset:64
	v_bfe_u32 v32, v33, 16, 1
	v_add3_u32 v32, v33, v32, s79
	ds_write_b16_d16_hi v49, v32 offset:64
	v_bfe_u32 v33, v34, 16, 1
	v_add3_u32 v32, v34, v33, s79
	ds_write_b16_d16_hi v50, v32 offset:64
	v_bfe_u32 v33, v35, 16, 1
	v_add3_u32 v32, v35, v33, s79
	ds_write_b16_d16_hi v51, v32 offset:64
	v_bfe_u32 v33, v36, 16, 1
	v_add3_u32 v32, v36, v33, s79
	ds_write_b16_d16_hi v52, v32 offset:64
	v_bfe_u32 v33, v37, 16, 1
	v_add3_u32 v32, v37, v33, s79
	ds_write_b16_d16_hi v53, v32 offset:64
	v_bfe_u32 v33, v38, 16, 1
	v_add3_u32 v32, v38, v33, s79
	ds_write_b16_d16_hi v54, v32 offset:64
	v_bfe_u32 v33, v39, 16, 1
	v_add3_u32 v32, v39, v33, s79
	ds_write_b16_d16_hi v56, v32 offset:64
	v_bfe_u32 v33, v40, 16, 1
	v_add3_u32 v32, v40, v33, s79
	ds_write_b16_d16_hi v57, v32 offset:64
	v_bfe_u32 v33, v41, 16, 1
	v_add3_u32 v32, v41, v33, s79
	ds_write_b16_d16_hi v58, v32 offset:64
	v_bfe_u32 v33, v42, 16, 1
	v_add3_u32 v32, v42, v33, s79
	ds_write_b16_d16_hi v59, v32 offset:64
	v_bfe_u32 v33, v43, 16, 1
	v_add3_u32 v32, v43, v33, s79
	ds_write_b16_d16_hi v60, v32 offset:64
	v_bfe_u32 v33, v44, 16, 1
	v_add3_u32 v32, v44, v33, s79
	ds_write_b16_d16_hi v61, v32 offset:64
	v_bfe_u32 v33, v45, 16, 1
	v_add3_u32 v32, v45, v33, s79
	ds_write_b16_d16_hi v62, v32 offset:64
	v_bfe_u32 v33, v46, 16, 1
	v_add3_u32 v32, v46, v33, s79
	ds_write_b16_d16_hi v55, v32 offset:64
	v_mov_b32_e32 v32, v47
	s_branch .LBB0_3225

; __device__ __forceinline__ float sigmf(float x) { return 1.f / (1.f + __expf(-x)); }
; template <int MT, int NT, class F>
; __device__ __forceinline__ void acc_foreach(int tid, f32x16 (&acc)[MT][NT], F f) {
;     ...
; #pragma unroll
;   for (int mt = 0; mt < MT; mt++)
; #pragma unroll
;     for (int nt = 0; nt < NT; nt++)
; #pragma unroll
;       for (int i = 0; i < 16; i++) {
;         int row = wm * (MT * 32) + mt * 32 + (i & 3) + 8 * (i >> 2) + 4 * hi;
;         int col = wn * (NT * 32) + nt * 32 + c;
;         f(row, col, acc[mt][nt][i]);
;         if (i == 15) __builtin_amdgcn_sched_barrier(0);
;       }
; __device__ __forceinline__ void inproj_epilogue(const Params& p, int layer, int mt, int ntile, int tid,
;                                                 f32x16 (&acc)[2][2], unsigned char* smem) {
;     ...
;     acc_foreach(tid, acc, [&](int row, int col, float v) {
;       int t = m0 + row;
;       float o = v;
;       if (mode == 1) o = (t >= NPADR) ? v : 0.f;
;       if (mode == 2) o = sigmf(v);
;       sT[row * 136 + col] = f2bf(o);
;     });
.Lfp_7:
	v_bfe_u32 v110, v16, 16, 1
	v_and_b32_e32 v106, 0x5f, v106
	v_add3_u32 v111, v16, v110, s83
	v_mul_lo_u32 v110, v96, s90
	v_lshl_add_u32 v107, v106, 1, v110
	ds_write_b16_d16_hi v107, v111
	v_add3_u32 v111, s88, v96, 1
	v_cmp_lt_i32_e64 s[10:11], s81, v111
	v_bfe_u32 v112, v17, 16, 1
	v_add3_u32 v112, v17, v112, s83
	v_add_u32_e32 v111, 0x110, v110
	v_lshl_add_u32 v110, v106, 1, v111
	ds_write_b16_d16_hi v110, v112
	v_bfe_u32 v113, v18, 16, 1
	v_add3_u32 v113, v18, v113, s83
	v_add_u32_e32 v112, 0x110, v111
	v_lshl_add_u32 v111, v106, 1, v112
	ds_write_b16_d16_hi v111, v113
	v_bfe_u32 v114, v19, 16, 1
	v_add3_u32 v114, v19, v114, s83
	v_add_u32_e32 v113, 0x110, v112
	v_lshl_add_u32 v112, v106, 1, v113
	ds_write_b16_d16_hi v112, v114
	v_bfe_u32 v115, v20, 16, 1
	v_add3_u32 v115, v20, v115, s83
	v_add_u32_e32 v114, 0x550, v113
	v_lshl_add_u32 v113, v106, 1, v114
	ds_write_b16_d16_hi v113, v115
	v_bfe_u32 v116, v21, 16, 1
	v_add3_u32 v116, v21, v116, s83
	v_add_u32_e32 v115, 0x110, v114
	v_lshl_add_u32 v114, v106, 1, v115
	ds_write_b16_d16_hi v114, v116
	v_bfe_u32 v117, v22, 16, 1
	v_add3_u32 v117, v22, v117, s83
	v_add_u32_e32 v116, 0x110, v115
	v_lshl_add_u32 v115, v106, 1, v116
	ds_write_b16_d16_hi v115, v117
	v_bfe_u32 v118, v23, 16, 1
	v_add_u32_e32 v116, 0x110, v116
	v_add3_u32 v118, v23, v118, s83
	v_lshl_add_u32 v117, v106, 1, v116
	ds_write_b16_d16_hi v117, v118
	v_bfe_u32 v119, v24, 16, 1
	v_add_u32_e32 v116, 0x550, v116
	v_add3_u32 v119, v24, v119, s83
	v_lshl_add_u32 v118, v106, 1, v116
	ds_write_b16_d16_hi v118, v119
	v_bfe_u32 v120, v25, 16, 1
	v_add_u32_e32 v116, 0x110, v116
	v_add3_u32 v120, v25, v120, s83
	v_lshl_add_u32 v119, v106, 1, v116
	ds_write_b16_d16_hi v119, v120
	v_bfe_u32 v121, v26, 16, 1
	v_add_u32_e32 v116, 0x110, v116
	v_add3_u32 v121, v26, v121, s83
	v_lshl_add_u32 v120, v106, 1, v116
	ds_write_b16_d16_hi v120, v121
	v_bfe_u32 v122, v27, 16, 1
	v_add_u32_e32 v116, 0x110, v116
	v_add3_u32 v122, v27, v122, s83
	v_lshl_add_u32 v121, v106, 1, v116
	ds_write_b16_d16_hi v121, v122
	v_bfe_u32 v123, v28, 16, 1
	v_add_u32_e32 v116, 0x550, v116
	v_add3_u32 v123, v28, v123, s83
	v_lshl_add_u32 v122, v106, 1, v116
	ds_write_b16_d16_hi v122, v123
	v_bfe_u32 v124, v29, 16, 1
	v_add_u32_e32 v116, 0x110, v116
	v_add3_u32 v124, v29, v124, s83
	v_lshl_add_u32 v123, v106, 1, v116
	ds_write_b16_d16_hi v123, v124
	v_bfe_u32 v125, v30, 16, 1
	v_add_u32_e32 v116, 0x110, v116
	v_add3_u32 v124, v30, v125, s83
	v_lshl_add_u32 v116, v106, 1, v116
	ds_write_b16_d16_hi v116, v124
	v_bfe_u32 v125, v31, 16, 1
	v_add3_u32 v124, v31, v125, s83
	ds_write_b16_d16_hi v116, v124 offset:272
	v_bfe_u32 v124, v48, 16, 1
	v_add3_u32 v48, v48, v124, s83
	ds_write_b16_d16_hi v107, v48 offset:64
	v_bfe_u32 v48, v49, 16, 1
	v_add3_u32 v48, v49, v48, s83
	ds_write_b16_d16_hi v110, v48 offset:64
	v_bfe_u32 v49, v50, 16, 1
	v_add3_u32 v48, v50, v49, s83
	ds_write_b16_d16_hi v111, v48 offset:64
	v_bfe_u32 v49, v51, 16, 1
	v_add3_u32 v48, v51, v49, s83
	ds_write_b16_d16_hi v112, v48 offset:64
	v_bfe_u32 v49, v52, 16, 1
	v_add3_u32 v48, v52, v49, s83
	ds_write_b16_d16_hi v113, v48 offset:64
	v_bfe_u32 v49, v53, 16, 1
	v_add3_u32 v48, v53, v49, s83
	ds_write_b16_d16_hi v114, v48 offset:64
	v_bfe_u32 v49, v54, 16, 1
	v_add3_u32 v48, v54, v49, s83
	ds_write_b16_d16_hi v115, v48 offset:64
	v_bfe_u32 v49, v55, 16, 1
	v_add3_u32 v48, v55, v49, s83
	ds_write_b16_d16_hi v117, v48 offset:64
	v_bfe_u32 v49, v56, 16, 1
	v_add3_u32 v48, v56, v49, s83
	ds_write_b16_d16_hi v118, v48 offset:64
	v_bfe_u32 v49, v57, 16, 1
	v_add3_u32 v48, v57, v49, s83
	ds_write_b16_d16_hi v119, v48 offset:64
	v_bfe_u32 v49, v58, 16, 1
	v_add3_u32 v48, v58, v49, s83
	ds_write_b16_d16_hi v120, v48 offset:64
	v_bfe_u32 v49, v59, 16, 1
	v_add3_u32 v48, v59, v49, s83
	ds_write_b16_d16_hi v121, v48 offset:64
	v_bfe_u32 v49, v60, 16, 1
	v_add3_u32 v48, v60, v49, s83
	ds_write_b16_d16_hi v122, v48 offset:64
	v_bfe_u32 v49, v61, 16, 1
	v_add3_u32 v48, v61, v49, s83
	ds_write_b16_d16_hi v123, v48 offset:64
	v_bfe_u32 v49, v62, 16, 1
	v_add3_u32 v48, v62, v49, s83
	ds_write_b16_d16_hi v116, v48 offset:64
; __device__ __forceinline__ float sigmf(float x) { return 1.f / (1.f + __expf(-x)); }
; template <int MT, int NT, class F>
; __device__ __forceinline__ void acc_foreach(int tid, f32x16 (&acc)[MT][NT], F f) {
;     ...
; #pragma unroll
;   for (int mt = 0; mt < MT; mt++)
; #pragma unroll
;     for (int nt = 0; nt < NT; nt++)
; #pragma unroll
;       for (int i = 0; i < 16; i++) {
;         int row = wm * (MT * 32) + mt * 32 + (i & 3) + 8 * (i >> 2) + 4 * hi;
;         int col = wn * (NT * 32) + nt * 32 + c;
;         f(row, col, acc[mt][nt][i]);
;         if (i == 15) __builtin_amdgcn_sched_barrier(0);
;       }
; __device__ __forceinline__ void inproj_epilogue(const Params& p, int layer, int mt, int ntile, int tid,
;                                                 f32x16 (&acc)[2][2], unsigned char* smem) {
;     ...
;     acc_foreach(tid, acc, [&](int row, int col, float v) {
;       int t = m0 + row;
;       float o = v;
;       if (mode == 1) o = (t >= NPADR) ? v : 0.f;
;       if (mode == 2) o = sigmf(v);
;       sT[row * 136 + col] = f2bf(o);
;     });
	v_bfe_u32 v50, v63, 16, 1
	v_add_u32_e32 v49, 0x110, v116
	v_add3_u32 v48, v63, v50, s83
	ds_write_b16_d16_hi v49, v48 offset:64
	v_or_b32_e32 v48, 32, v96
	v_add_u32_e32 v49, s88, v48
	v_cmp_lt_i32_e64 s[8:9], s81, v49
	v_bfe_u32 v50, v0, 16, 1
	v_add3_u32 v50, v0, v50, s83
	v_mul_lo_u32 v49, v48, s90
	v_lshl_add_u32 v48, v106, 1, v49
	ds_write_b16_d16_hi v48, v50
	v_bfe_u32 v51, v1, 16, 1
	v_add3_u32 v51, v1, v51, s83
	v_add_u32_e32 v50, 0x110, v49
	v_lshl_add_u32 v49, v106, 1, v50
	ds_write_b16_d16_hi v49, v51
	v_bfe_u32 v52, v2, 16, 1
	v_add3_u32 v52, v2, v52, s83
	v_add_u32_e32 v51, 0x110, v50
	v_lshl_add_u32 v50, v106, 1, v51
	ds_write_b16_d16_hi v50, v52
	v_bfe_u32 v53, v3, 16, 1
	v_add3_u32 v53, v3, v53, s83
	v_add_u32_e32 v52, 0x110, v51
	v_lshl_add_u32 v51, v106, 1, v52
	ds_write_b16_d16_hi v51, v53
	v_bfe_u32 v54, v4, 16, 1
	v_add3_u32 v54, v4, v54, s83
	v_add_u32_e32 v53, 0x550, v52
	v_lshl_add_u32 v52, v106, 1, v53
	ds_write_b16_d16_hi v52, v54
	v_bfe_u32 v55, v5, 16, 1
	v_add3_u32 v55, v5, v55, s83
	v_add_u32_e32 v54, 0x110, v53
	v_lshl_add_u32 v53, v106, 1, v54
	ds_write_b16_d16_hi v53, v55
	v_bfe_u32 v56, v6, 16, 1
	v_add3_u32 v56, v6, v56, s83
	v_add_u32_e32 v55, 0x110, v54
	v_lshl_add_u32 v54, v106, 1, v55
	ds_write_b16_d16_hi v54, v56
	v_bfe_u32 v57, v7, 16, 1
	v_add_u32_e32 v55, 0x110, v55
	v_add3_u32 v57, v7, v57, s83
	v_lshl_add_u32 v56, v106, 1, v55
	ds_write_b16_d16_hi v56, v57
	v_bfe_u32 v58, v8, 16, 1
	v_add_u32_e32 v55, 0x550, v55
	v_add3_u32 v58, v8, v58, s83
	v_lshl_add_u32 v57, v106, 1, v55
	ds_write_b16_d16_hi v57, v58
	v_bfe_u32 v59, v9, 16, 1
	v_add_u32_e32 v55, 0x110, v55
	v_add3_u32 v59, v9, v59, s83
	v_lshl_add_u32 v58, v106, 1, v55
	ds_write_b16_d16_hi v58, v59
	v_bfe_u32 v60, v10, 16, 1
	v_add_u32_e32 v55, 0x110, v55
	v_add3_u32 v60, v10, v60, s83
	v_lshl_add_u32 v59, v106, 1, v55
	ds_write_b16_d16_hi v59, v60
	v_bfe_u32 v61, v11, 16, 1
	v_add_u32_e32 v55, 0x110, v55
	v_add3_u32 v61, v11, v61, s83
	v_lshl_add_u32 v60, v106, 1, v55
	ds_write_b16_d16_hi v60, v61
	v_bfe_u32 v62, v12, 16, 1
	v_add_u32_e32 v55, 0x550, v55
	v_add3_u32 v62, v12, v62, s83
	v_lshl_add_u32 v61, v106, 1, v55
	ds_write_b16_d16_hi v61, v62
	v_bfe_u32 v63, v13, 16, 1
	v_add_u32_e32 v55, 0x110, v55
	v_add3_u32 v63, v13, v63, s83
	v_lshl_add_u32 v62, v106, 1, v55
	ds_write_b16_d16_hi v62, v63
	v_bfe_u32 v107, v14, 16, 1
	v_add_u32_e32 v55, 0x110, v55
	v_add3_u32 v63, v14, v107, s83
	v_lshl_add_u32 v55, v106, 1, v55
	ds_write_b16_d16_hi v55, v63
	v_bfe_u32 v96, v15, 16, 1
	v_add3_u32 v63, v15, v96, s83
	ds_write_b16_d16_hi v55, v63 offset:272
	v_bfe_u32 v63, v32, 16, 1
	v_add3_u32 v32, v32, v63, s83
	ds_write_b16_d16_hi v48, v32 offset:64
	v_bfe_u32 v32, v33, 16, 1
	v_add3_u32 v32, v33, v32, s83
	ds_write_b16_d16_hi v49, v32 offset:64
	v_bfe_u32 v33, v34, 16, 1
	v_add3_u32 v32, v34, v33, s83
	ds_write_b16_d16_hi v50, v32 offset:64
	v_bfe_u32 v33, v35, 16, 1
	v_add3_u32 v32, v35, v33, s83
	ds_write_b16_d16_hi v51, v32 offset:64
	v_bfe_u32 v33, v36, 16, 1
	v_add3_u32 v32, v36, v33, s83
	ds_write_b16_d16_hi v52, v32 offset:64
	v_bfe_u32 v33, v37, 16, 1
	v_add3_u32 v32, v37, v33, s83
	ds_write_b16_d16_hi v53, v32 offset:64
	v_bfe_u32 v33, v38, 16, 1
	v_add3_u32 v32, v38, v33, s83
	ds_write_b16_d16_hi v54, v32 offset:64
	v_bfe_u32 v33, v39, 16, 1
	v_add3_u32 v32, v39, v33, s83
	ds_write_b16_d16_hi v56, v32 offset:64
	v_bfe_u32 v33, v40, 16, 1
	v_add3_u32 v32, v40, v33, s83
	ds_write_b16_d16_hi v57, v32 offset:64
	v_bfe_u32 v33, v41, 16, 1
	v_add3_u32 v32, v41, v33, s83
	ds_write_b16_d16_hi v58, v32 offset:64
	v_bfe_u32 v33, v42, 16, 1
	v_add3_u32 v32, v42, v33, s83
	ds_write_b16_d16_hi v59, v32 offset:64
	v_bfe_u32 v33, v43, 16, 1
	v_add3_u32 v32, v43, v33, s83
	ds_write_b16_d16_hi v60, v32 offset:64
	v_bfe_u32 v33, v44, 16, 1
	v_add3_u32 v32, v44, v33, s83
	ds_write_b16_d16_hi v61, v32 offset:64
	v_bfe_u32 v33, v45, 16, 1
	v_add3_u32 v32, v45, v33, s83
	ds_write_b16_d16_hi v62, v32 offset:64
	v_bfe_u32 v33, v46, 16, 1
	v_add3_u32 v32, v46, v33, s83
	ds_write_b16_d16_hi v55, v32 offset:64
	v_mov_b32_e32 v32, v47
	s_branch .LBB0_3559

; __device__ __forceinline__ float sigmf(float x) { return 1.f / (1.f + __expf(-x)); }
; template <int MT, int NT, class F>
; __device__ __forceinline__ void acc_foreach(int tid, f32x16 (&acc)[MT][NT], F f) {
;     ...
; #pragma unroll
;   for (int mt = 0; mt < MT; mt++)
; #pragma unroll
;     for (int nt = 0; nt < NT; nt++)
; #pragma unroll
;       for (int i = 0; i < 16; i++) {
;         int row = wm * (MT * 32) + mt * 32 + (i & 3) + 8 * (i >> 2) + 4 * hi;
;         int col = wn * (NT * 32) + nt * 32 + c;
;         f(row, col, acc[mt][nt][i]);
; __device__ __forceinline__ void inproj_epilogue(const Params& p, int layer, int mt, int ntile, int tid,
;                                                 f32x16 (&acc)[2][2], unsigned char* smem) {
;     ...
;     acc_foreach(tid, acc, [&](int row, int col, float v) {
;       int t = m0 + row;
;       float o = v;
;       if (mode == 1) o = (t >= NPADR) ? v : 0.f;
;       if (mode == 2) o = sigmf(v);
;       sT[row * 136 + col] = f2bf(o);
;     });
.Lfp_8:
	v_bfe_u32 v110, v16, 16, 1
	v_and_b32_e32 v106, 0x5f, v106
	v_add3_u32 v111, v16, v110, s80
	v_mul_lo_u32 v110, v96, s81
	v_lshl_add_u32 v107, v106, 1, v110
	ds_write_b16_d16_hi v107, v111
	v_add3_u32 v111, s74, v96, 1
	v_cmp_lt_i32_e64 s[10:11], s78, v111
	v_bfe_u32 v112, v17, 16, 1
	v_add3_u32 v112, v17, v112, s80
	v_add_u32_e32 v111, 0x110, v110
	v_lshl_add_u32 v110, v106, 1, v111
	ds_write_b16_d16_hi v110, v112
	v_bfe_u32 v113, v18, 16, 1
	v_add3_u32 v113, v18, v113, s80
	v_add_u32_e32 v112, 0x110, v111
	v_lshl_add_u32 v111, v106, 1, v112
	ds_write_b16_d16_hi v111, v113
	v_bfe_u32 v114, v19, 16, 1
	v_add3_u32 v114, v19, v114, s80
	v_add_u32_e32 v113, 0x110, v112
	v_lshl_add_u32 v112, v106, 1, v113
	ds_write_b16_d16_hi v112, v114
	v_bfe_u32 v115, v20, 16, 1
	v_add3_u32 v115, v20, v115, s80
	v_add_u32_e32 v114, 0x550, v113
	v_lshl_add_u32 v113, v106, 1, v114
	ds_write_b16_d16_hi v113, v115
	v_bfe_u32 v116, v21, 16, 1
	v_add3_u32 v116, v21, v116, s80
	v_add_u32_e32 v115, 0x110, v114
	v_lshl_add_u32 v114, v106, 1, v115
	ds_write_b16_d16_hi v114, v116
	v_bfe_u32 v117, v22, 16, 1
	v_add3_u32 v117, v22, v117, s80
	v_add_u32_e32 v116, 0x110, v115
	v_lshl_add_u32 v115, v106, 1, v116
	ds_write_b16_d16_hi v115, v117
	v_bfe_u32 v118, v23, 16, 1
	v_add_u32_e32 v116, 0x110, v116
	v_add3_u32 v118, v23, v118, s80
	v_lshl_add_u32 v117, v106, 1, v116
	ds_write_b16_d16_hi v117, v118
	v_bfe_u32 v119, v24, 16, 1
	v_add_u32_e32 v116, 0x550, v116
	v_add3_u32 v119, v24, v119, s80
	v_lshl_add_u32 v118, v106, 1, v116
	ds_write_b16_d16_hi v118, v119
	v_bfe_u32 v120, v25, 16, 1
	v_add_u32_e32 v116, 0x110, v116
	v_add3_u32 v120, v25, v120, s80
	v_lshl_add_u32 v119, v106, 1, v116
	ds_write_b16_d16_hi v119, v120
	v_bfe_u32 v121, v26, 16, 1
	v_add_u32_e32 v116, 0x110, v116
	v_add3_u32 v121, v26, v121, s80
	v_lshl_add_u32 v120, v106, 1, v116
	ds_write_b16_d16_hi v120, v121
	v_bfe_u32 v122, v27, 16, 1
	v_add_u32_e32 v116, 0x110, v116
	v_add3_u32 v122, v27, v122, s80
	v_lshl_add_u32 v121, v106, 1, v116
	ds_write_b16_d16_hi v121, v122
	v_bfe_u32 v123, v28, 16, 1
	v_add_u32_e32 v116, 0x550, v116
	v_add3_u32 v123, v28, v123, s80
	v_lshl_add_u32 v122, v106, 1, v116
	ds_write_b16_d16_hi v122, v123
	v_bfe_u32 v124, v29, 16, 1
	v_add_u32_e32 v116, 0x110, v116
	v_add3_u32 v124, v29, v124, s80
	v_lshl_add_u32 v123, v106, 1, v116
	ds_write_b16_d16_hi v123, v124
	v_bfe_u32 v125, v30, 16, 1
	v_add_u32_e32 v116, 0x110, v116
	v_add3_u32 v124, v30, v125, s80
	v_lshl_add_u32 v116, v106, 1, v116
	ds_write_b16_d16_hi v116, v124
	v_bfe_u32 v125, v31, 16, 1
	v_add3_u32 v124, v31, v125, s80
	ds_write_b16_d16_hi v116, v124 offset:272
	v_bfe_u32 v124, v48, 16, 1
	v_add3_u32 v48, v48, v124, s80
	ds_write_b16_d16_hi v107, v48 offset:64
	v_bfe_u32 v48, v49, 16, 1
	v_add3_u32 v48, v49, v48, s80
	ds_write_b16_d16_hi v110, v48 offset:64
	v_bfe_u32 v49, v50, 16, 1
	v_add3_u32 v48, v50, v49, s80
	ds_write_b16_d16_hi v111, v48 offset:64
	v_bfe_u32 v49, v51, 16, 1
	v_add3_u32 v48, v51, v49, s80
	ds_write_b16_d16_hi v112, v48 offset:64
	v_bfe_u32 v49, v52, 16, 1
	v_add3_u32 v48, v52, v49, s80
	ds_write_b16_d16_hi v113, v48 offset:64
	v_bfe_u32 v49, v53, 16, 1
	v_add3_u32 v48, v53, v49, s80
	ds_write_b16_d16_hi v114, v48 offset:64
	v_bfe_u32 v49, v54, 16, 1
	v_add3_u32 v48, v54, v49, s80
	ds_write_b16_d16_hi v115, v48 offset:64
	v_bfe_u32 v49, v55, 16, 1
	v_add3_u32 v48, v55, v49, s80
	ds_write_b16_d16_hi v117, v48 offset:64
	v_bfe_u32 v49, v56, 16, 1
	v_add3_u32 v48, v56, v49, s80
	ds_write_b16_d16_hi v118, v48 offset:64
	v_bfe_u32 v49, v57, 16, 1
	v_add3_u32 v48, v57, v49, s80
	ds_write_b16_d16_hi v119, v48 offset:64
	v_bfe_u32 v49, v58, 16, 1
	v_add3_u32 v48, v58, v49, s80
	ds_write_b16_d16_hi v120, v48 offset:64
	v_bfe_u32 v49, v59, 16, 1
	v_add3_u32 v48, v59, v49, s80
	ds_write_b16_d16_hi v121, v48 offset:64
	v_bfe_u32 v49, v60, 16, 1
	v_add3_u32 v48, v60, v49, s80
	ds_write_b16_d16_hi v122, v48 offset:64
	v_bfe_u32 v49, v61, 16, 1
	v_add3_u32 v48, v61, v49, s80
	ds_write_b16_d16_hi v123, v48 offset:64
	v_bfe_u32 v49, v62, 16, 1
	v_add3_u32 v48, v62, v49, s80
	ds_write_b16_d16_hi v116, v48 offset:64
; __device__ __forceinline__ float sigmf(float x) { return 1.f / (1.f + __expf(-x)); }
; template <int MT, int NT, class F>
; __device__ __forceinline__ void acc_foreach(int tid, f32x16 (&acc)[MT][NT], F f) {
;     ...
; #pragma unroll
;   for (int mt = 0; mt < MT; mt++)
; #pragma unroll
;     for (int nt = 0; nt < NT; nt++)
; #pragma unroll
;       for (int i = 0; i < 16; i++) {
;         int row = wm * (MT * 32) + mt * 32 + (i & 3) + 8 * (i >> 2) + 4 * hi;
;         int col = wn * (NT * 32) + nt * 32 + c;
;         f(row, col, acc[mt][nt][i]);
; __device__ __forceinline__ void inproj_epilogue(const Params& p, int layer, int mt, int ntile, int tid,
;                                                 f32x16 (&acc)[2][2], unsigned char* smem) {
;     ...
;     acc_foreach(tid, acc, [&](int row, int col, float v) {
;       int t = m0 + row;
;       float o = v;
;       if (mode == 1) o = (t >= NPADR) ? v : 0.f;
;       if (mode == 2) o = sigmf(v);
;       sT[row * 136 + col] = f2bf(o);
;     });
	v_bfe_u32 v50, v63, 16, 1
	v_add_u32_e32 v49, 0x110, v116
	v_add3_u32 v48, v63, v50, s80
	ds_write_b16_d16_hi v49, v48 offset:64
	v_or_b32_e32 v48, 32, v96
	v_add_u32_e32 v49, s74, v48
	v_cmp_lt_i32_e64 s[8:9], s78, v49
	v_bfe_u32 v50, v0, 16, 1
	v_add3_u32 v50, v0, v50, s80
	v_mul_lo_u32 v49, v48, s81
	v_lshl_add_u32 v48, v106, 1, v49
	ds_write_b16_d16_hi v48, v50
	v_bfe_u32 v51, v1, 16, 1
	v_add3_u32 v51, v1, v51, s80
	v_add_u32_e32 v50, 0x110, v49
	v_lshl_add_u32 v49, v106, 1, v50
	ds_write_b16_d16_hi v49, v51
	v_bfe_u32 v52, v2, 16, 1
	v_add3_u32 v52, v2, v52, s80
	v_add_u32_e32 v51, 0x110, v50
	v_lshl_add_u32 v50, v106, 1, v51
	ds_write_b16_d16_hi v50, v52
	v_bfe_u32 v53, v3, 16, 1
	v_add3_u32 v53, v3, v53, s80
	v_add_u32_e32 v52, 0x110, v51
	v_lshl_add_u32 v51, v106, 1, v52
	ds_write_b16_d16_hi v51, v53
	v_bfe_u32 v54, v4, 16, 1
	v_add3_u32 v54, v4, v54, s80
	v_add_u32_e32 v53, 0x550, v52
	v_lshl_add_u32 v52, v106, 1, v53
	ds_write_b16_d16_hi v52, v54
	v_bfe_u32 v55, v5, 16, 1
	v_add3_u32 v55, v5, v55, s80
	v_add_u32_e32 v54, 0x110, v53
	v_lshl_add_u32 v53, v106, 1, v54
	ds_write_b16_d16_hi v53, v55
	v_bfe_u32 v56, v6, 16, 1
	v_add3_u32 v56, v6, v56, s80
	v_add_u32_e32 v55, 0x110, v54
	v_lshl_add_u32 v54, v106, 1, v55
	ds_write_b16_d16_hi v54, v56
	v_bfe_u32 v57, v7, 16, 1
	v_add_u32_e32 v55, 0x110, v55
	v_add3_u32 v57, v7, v57, s80
	v_lshl_add_u32 v56, v106, 1, v55
	ds_write_b16_d16_hi v56, v57
	v_bfe_u32 v58, v8, 16, 1
	v_add_u32_e32 v55, 0x550, v55
	v_add3_u32 v58, v8, v58, s80
	v_lshl_add_u32 v57, v106, 1, v55
	ds_write_b16_d16_hi v57, v58
	v_bfe_u32 v59, v9, 16, 1
	v_add_u32_e32 v55, 0x110, v55
	v_add3_u32 v59, v9, v59, s80
	v_lshl_add_u32 v58, v106, 1, v55
	ds_write_b16_d16_hi v58, v59
	v_bfe_u32 v60, v10, 16, 1
	v_add_u32_e32 v55, 0x110, v55
	v_add3_u32 v60, v10, v60, s80
	v_lshl_add_u32 v59, v106, 1, v55
	ds_write_b16_d16_hi v59, v60
	v_bfe_u32 v61, v11, 16, 1
	v_add_u32_e32 v55, 0x110, v55
	v_add3_u32 v61, v11, v61, s80
	v_lshl_add_u32 v60, v106, 1, v55
	ds_write_b16_d16_hi v60, v61
	v_bfe_u32 v62, v12, 16, 1
	v_add_u32_e32 v55, 0x550, v55
	v_add3_u32 v62, v12, v62, s80
	v_lshl_add_u32 v61, v106, 1, v55
	ds_write_b16_d16_hi v61, v62
	v_bfe_u32 v63, v13, 16, 1
	v_add_u32_e32 v55, 0x110, v55
	v_add3_u32 v63, v13, v63, s80
	v_lshl_add_u32 v62, v106, 1, v55
	ds_write_b16_d16_hi v62, v63
	v_bfe_u32 v107, v14, 16, 1
	v_add_u32_e32 v55, 0x110, v55
	v_add3_u32 v63, v14, v107, s80
	v_lshl_add_u32 v55, v106, 1, v55
	ds_write_b16_d16_hi v55, v63
	v_bfe_u32 v96, v15, 16, 1
	v_add3_u32 v63, v15, v96, s80
	ds_write_b16_d16_hi v55, v63 offset:272
	v_bfe_u32 v63, v32, 16, 1
	v_add3_u32 v32, v32, v63, s80
	ds_write_b16_d16_hi v48, v32 offset:64
	v_bfe_u32 v32, v33, 16, 1
	v_add3_u32 v32, v33, v32, s80
	ds_write_b16_d16_hi v49, v32 offset:64
	v_bfe_u32 v33, v34, 16, 1
	v_add3_u32 v32, v34, v33, s80
	ds_write_b16_d16_hi v50, v32 offset:64
	v_bfe_u32 v33, v35, 16, 1
	v_add3_u32 v32, v35, v33, s80
	ds_write_b16_d16_hi v51, v32 offset:64
	v_bfe_u32 v33, v36, 16, 1
	v_add3_u32 v32, v36, v33, s80
	ds_write_b16_d16_hi v52, v32 offset:64
	v_bfe_u32 v33, v37, 16, 1
	v_add3_u32 v32, v37, v33, s80
	ds_write_b16_d16_hi v53, v32 offset:64
	v_bfe_u32 v33, v38, 16, 1
	v_add3_u32 v32, v38, v33, s80
	ds_write_b16_d16_hi v54, v32 offset:64
	v_bfe_u32 v33, v39, 16, 1
	v_add3_u32 v32, v39, v33, s80
	ds_write_b16_d16_hi v56, v32 offset:64
	v_bfe_u32 v33, v40, 16, 1
	v_add3_u32 v32, v40, v33, s80
	ds_write_b16_d16_hi v57, v32 offset:64
	v_bfe_u32 v33, v41, 16, 1
	v_add3_u32 v32, v41, v33, s80
	ds_write_b16_d16_hi v58, v32 offset:64
	v_bfe_u32 v33, v42, 16, 1
	v_add3_u32 v32, v42, v33, s80
	ds_write_b16_d16_hi v59, v32 offset:64
	v_bfe_u32 v33, v43, 16, 1
	v_add3_u32 v32, v43, v33, s80
	ds_write_b16_d16_hi v60, v32 offset:64
	v_bfe_u32 v33, v44, 16, 1
	v_add3_u32 v32, v44, v33, s80
	ds_write_b16_d16_hi v61, v32 offset:64
	v_bfe_u32 v33, v45, 16, 1
	v_add3_u32 v32, v45, v33, s80
	ds_write_b16_d16_hi v62, v32 offset:64
	v_bfe_u32 v33, v46, 16, 1
	v_add3_u32 v32, v46, v33, s80
	ds_write_b16_d16_hi v55, v32 offset:64
	v_mov_b32_e32 v32, v47
	s_branch .LBB0_4343

; __device__ __forceinline__ float sigmf(float x) { return 1.f / (1.f + __expf(-x)); }
; template <int MT, int NT, class F>
; __device__ __forceinline__ void acc_foreach(int tid, f32x16 (&acc)[MT][NT], F f) {
;     ...
; #pragma unroll
;   for (int mt = 0; mt < MT; mt++)
; #pragma unroll
;     for (int nt = 0; nt < NT; nt++)
; #pragma unroll
;       for (int i = 0; i < 16; i++) {
;         int row = wm * (MT * 32) + mt * 32 + (i & 3) + 8 * (i >> 2) + 4 * hi;
;         int col = wn * (NT * 32) + nt * 32 + c;
;         f(row, col, acc[mt][nt][i]);
; __device__ __forceinline__ void inproj_epilogue(const Params& p, int layer, int mt, int ntile, int tid,
;                                                 f32x16 (&acc)[2][2], unsigned char* smem) {
;     ...
;     acc_foreach(tid, acc, [&](int row, int col, float v) {
;       int t = m0 + row;
;       float o = v;
;       if (mode == 1) o = (t >= NPADR) ? v : 0.f;
;       if (mode == 2) o = sigmf(v);
;       sT[row * 136 + col] = f2bf(o);
;     });
.Lfp_9:
	v_bfe_u32 v110, v16, 16, 1
	v_and_b32_e32 v106, 0x5f, v106
	v_add3_u32 v111, v16, v110, s83
	v_mul_lo_u32 v110, v96, s86
	v_lshl_add_u32 v107, v106, 1, v110
	ds_write_b16_d16_hi v107, v111
	v_add3_u32 v111, s74, v96, 1
	v_cmp_lt_i32_e64 s[10:11], s81, v111
	v_bfe_u32 v112, v17, 16, 1
	v_add3_u32 v112, v17, v112, s83
	v_add_u32_e32 v111, 0x110, v110
	v_lshl_add_u32 v110, v106, 1, v111
	ds_write_b16_d16_hi v110, v112
	v_bfe_u32 v113, v18, 16, 1
	v_add3_u32 v113, v18, v113, s83
	v_add_u32_e32 v112, 0x110, v111
	v_lshl_add_u32 v111, v106, 1, v112
	ds_write_b16_d16_hi v111, v113
	v_bfe_u32 v114, v19, 16, 1
	v_add3_u32 v114, v19, v114, s83
	v_add_u32_e32 v113, 0x110, v112
	v_lshl_add_u32 v112, v106, 1, v113
	ds_write_b16_d16_hi v112, v114
	v_bfe_u32 v115, v20, 16, 1
	v_add3_u32 v115, v20, v115, s83
	v_add_u32_e32 v114, 0x550, v113
	v_lshl_add_u32 v113, v106, 1, v114
	ds_write_b16_d16_hi v113, v115
	v_bfe_u32 v116, v21, 16, 1
	v_add3_u32 v116, v21, v116, s83
	v_add_u32_e32 v115, 0x110, v114
	v_lshl_add_u32 v114, v106, 1, v115
	ds_write_b16_d16_hi v114, v116
	v_bfe_u32 v117, v22, 16, 1
	v_add3_u32 v117, v22, v117, s83
	v_add_u32_e32 v116, 0x110, v115
	v_lshl_add_u32 v115, v106, 1, v116
	ds_write_b16_d16_hi v115, v117
	v_bfe_u32 v118, v23, 16, 1
	v_add_u32_e32 v116, 0x110, v116
	v_add3_u32 v118, v23, v118, s83
	v_lshl_add_u32 v117, v106, 1, v116
	ds_write_b16_d16_hi v117, v118
	v_bfe_u32 v119, v24, 16, 1
	v_add_u32_e32 v116, 0x550, v116
	v_add3_u32 v119, v24, v119, s83
	v_lshl_add_u32 v118, v106, 1, v116
	ds_write_b16_d16_hi v118, v119
	v_bfe_u32 v120, v25, 16, 1
	v_add_u32_e32 v116, 0x110, v116
	v_add3_u32 v120, v25, v120, s83
	v_lshl_add_u32 v119, v106, 1, v116
	ds_write_b16_d16_hi v119, v120
	v_bfe_u32 v121, v26, 16, 1
	v_add_u32_e32 v116, 0x110, v116
	v_add3_u32 v121, v26, v121, s83
	v_lshl_add_u32 v120, v106, 1, v116
	ds_write_b16_d16_hi v120, v121
	v_bfe_u32 v122, v27, 16, 1
	v_add_u32_e32 v116, 0x110, v116
	v_add3_u32 v122, v27, v122, s83
	v_lshl_add_u32 v121, v106, 1, v116
	ds_write_b16_d16_hi v121, v122
	v_bfe_u32 v123, v28, 16, 1
	v_add_u32_e32 v116, 0x550, v116
	v_add3_u32 v123, v28, v123, s83
	v_lshl_add_u32 v122, v106, 1, v116
	ds_write_b16_d16_hi v122, v123
	v_bfe_u32 v124, v29, 16, 1
	v_add_u32_e32 v116, 0x110, v116
	v_add3_u32 v124, v29, v124, s83
	v_lshl_add_u32 v123, v106, 1, v116
	ds_write_b16_d16_hi v123, v124
	v_bfe_u32 v125, v30, 16, 1
	v_add_u32_e32 v116, 0x110, v116
	v_add3_u32 v124, v30, v125, s83
	v_lshl_add_u32 v116, v106, 1, v116
	ds_write_b16_d16_hi v116, v124
	v_bfe_u32 v125, v31, 16, 1
	v_add3_u32 v124, v31, v125, s83
	ds_write_b16_d16_hi v116, v124 offset:272
	v_bfe_u32 v124, v48, 16, 1
	v_add3_u32 v48, v48, v124, s83
	ds_write_b16_d16_hi v107, v48 offset:64
	v_bfe_u32 v48, v49, 16, 1
	v_add3_u32 v48, v49, v48, s83
	ds_write_b16_d16_hi v110, v48 offset:64
	v_bfe_u32 v49, v50, 16, 1
	v_add3_u32 v48, v50, v49, s83
	ds_write_b16_d16_hi v111, v48 offset:64
	v_bfe_u32 v49, v51, 16, 1
	v_add3_u32 v48, v51, v49, s83
	ds_write_b16_d16_hi v112, v48 offset:64
	v_bfe_u32 v49, v52, 16, 1
	v_add3_u32 v48, v52, v49, s83
	ds_write_b16_d16_hi v113, v48 offset:64
	v_bfe_u32 v49, v53, 16, 1
	v_add3_u32 v48, v53, v49, s83
	ds_write_b16_d16_hi v114, v48 offset:64
	v_bfe_u32 v49, v54, 16, 1
	v_add3_u32 v48, v54, v49, s83
	ds_write_b16_d16_hi v115, v48 offset:64
	v_bfe_u32 v49, v55, 16, 1
	v_add3_u32 v48, v55, v49, s83
	ds_write_b16_d16_hi v117, v48 offset:64
	v_bfe_u32 v49, v56, 16, 1
	v_add3_u32 v48, v56, v49, s83
	ds_write_b16_d16_hi v118, v48 offset:64
	v_bfe_u32 v49, v57, 16, 1
	v_add3_u32 v48, v57, v49, s83
	ds_write_b16_d16_hi v119, v48 offset:64
	v_bfe_u32 v49, v58, 16, 1
	v_add3_u32 v48, v58, v49, s83
	ds_write_b16_d16_hi v120, v48 offset:64
	v_bfe_u32 v49, v59, 16, 1
	v_add3_u32 v48, v59, v49, s83
	ds_write_b16_d16_hi v121, v48 offset:64
	v_bfe_u32 v49, v60, 16, 1
	v_add3_u32 v48, v60, v49, s83
	ds_write_b16_d16_hi v122, v48 offset:64
	v_bfe_u32 v49, v61, 16, 1
	v_add3_u32 v48, v61, v49, s83
	ds_write_b16_d16_hi v123, v48 offset:64
	v_bfe_u32 v49, v62, 16, 1
	v_add3_u32 v48, v62, v49, s83
	ds_write_b16_d16_hi v116, v48 offset:64
; __device__ __forceinline__ float sigmf(float x) { return 1.f / (1.f + __expf(-x)); }
; template <int MT, int NT, class F>
; __device__ __forceinline__ void acc_foreach(int tid, f32x16 (&acc)[MT][NT], F f) {
;     ...
; #pragma unroll
;   for (int mt = 0; mt < MT; mt++)
; #pragma unroll
;     for (int nt = 0; nt < NT; nt++)
; #pragma unroll
;       for (int i = 0; i < 16; i++) {
;         int row = wm * (MT * 32) + mt * 32 + (i & 3) + 8 * (i >> 2) + 4 * hi;
;         int col = wn * (NT * 32) + nt * 32 + c;
;         f(row, col, acc[mt][nt][i]);
; __device__ __forceinline__ void inproj_epilogue(const Params& p, int layer, int mt, int ntile, int tid,
;                                                 f32x16 (&acc)[2][2], unsigned char* smem) {
;     ...
;     acc_foreach(tid, acc, [&](int row, int col, float v) {
;       int t = m0 + row;
;       float o = v;
;       if (mode == 1) o = (t >= NPADR) ? v : 0.f;
;       if (mode == 2) o = sigmf(v);
;       sT[row * 136 + col] = f2bf(o);
;     });
	v_bfe_u32 v50, v63, 16, 1
	v_add_u32_e32 v49, 0x110, v116
	v_add3_u32 v48, v63, v50, s83
	ds_write_b16_d16_hi v49, v48 offset:64
	v_or_b32_e32 v48, 32, v96
	v_add_u32_e32 v49, s74, v48
	v_cmp_lt_i32_e64 s[8:9], s81, v49
	v_bfe_u32 v50, v0, 16, 1
	v_add3_u32 v50, v0, v50, s83
	v_mul_lo_u32 v49, v48, s86
	v_lshl_add_u32 v48, v106, 1, v49
	ds_write_b16_d16_hi v48, v50
	v_bfe_u32 v51, v1, 16, 1
	v_add3_u32 v51, v1, v51, s83
	v_add_u32_e32 v50, 0x110, v49
	v_lshl_add_u32 v49, v106, 1, v50
	ds_write_b16_d16_hi v49, v51
	v_bfe_u32 v52, v2, 16, 1
	v_add3_u32 v52, v2, v52, s83
	v_add_u32_e32 v51, 0x110, v50
	v_lshl_add_u32 v50, v106, 1, v51
	ds_write_b16_d16_hi v50, v52
	v_bfe_u32 v53, v3, 16, 1
	v_add3_u32 v53, v3, v53, s83
	v_add_u32_e32 v52, 0x110, v51
	v_lshl_add_u32 v51, v106, 1, v52
	ds_write_b16_d16_hi v51, v53
	v_bfe_u32 v54, v4, 16, 1
	v_add3_u32 v54, v4, v54, s83
	v_add_u32_e32 v53, 0x550, v52
	v_lshl_add_u32 v52, v106, 1, v53
	ds_write_b16_d16_hi v52, v54
	v_bfe_u32 v55, v5, 16, 1
	v_add3_u32 v55, v5, v55, s83
	v_add_u32_e32 v54, 0x110, v53
	v_lshl_add_u32 v53, v106, 1, v54
	ds_write_b16_d16_hi v53, v55
	v_bfe_u32 v56, v6, 16, 1
	v_add3_u32 v56, v6, v56, s83
	v_add_u32_e32 v55, 0x110, v54
	v_lshl_add_u32 v54, v106, 1, v55
	ds_write_b16_d16_hi v54, v56
	v_bfe_u32 v57, v7, 16, 1
	v_add_u32_e32 v55, 0x110, v55
	v_add3_u32 v57, v7, v57, s83
	v_lshl_add_u32 v56, v106, 1, v55
	ds_write_b16_d16_hi v56, v57
	v_bfe_u32 v58, v8, 16, 1
	v_add_u32_e32 v55, 0x550, v55
	v_add3_u32 v58, v8, v58, s83
	v_lshl_add_u32 v57, v106, 1, v55
	ds_write_b16_d16_hi v57, v58
	v_bfe_u32 v59, v9, 16, 1
	v_add_u32_e32 v55, 0x110, v55
	v_add3_u32 v59, v9, v59, s83
	v_lshl_add_u32 v58, v106, 1, v55
	ds_write_b16_d16_hi v58, v59
	v_bfe_u32 v60, v10, 16, 1
	v_add_u32_e32 v55, 0x110, v55
	v_add3_u32 v60, v10, v60, s83
	v_lshl_add_u32 v59, v106, 1, v55
	ds_write_b16_d16_hi v59, v60
	v_bfe_u32 v61, v11, 16, 1
	v_add_u32_e32 v55, 0x110, v55
	v_add3_u32 v61, v11, v61, s83
	v_lshl_add_u32 v60, v106, 1, v55
	ds_write_b16_d16_hi v60, v61
	v_bfe_u32 v62, v12, 16, 1
	v_add_u32_e32 v55, 0x550, v55
	v_add3_u32 v62, v12, v62, s83
	v_lshl_add_u32 v61, v106, 1, v55
	ds_write_b16_d16_hi v61, v62
	v_bfe_u32 v63, v13, 16, 1
	v_add_u32_e32 v55, 0x110, v55
	v_add3_u32 v63, v13, v63, s83
	v_lshl_add_u32 v62, v106, 1, v55
	ds_write_b16_d16_hi v62, v63
	v_bfe_u32 v107, v14, 16, 1
	v_add_u32_e32 v55, 0x110, v55
	v_add3_u32 v63, v14, v107, s83
	v_lshl_add_u32 v55, v106, 1, v55
	ds_write_b16_d16_hi v55, v63
	v_bfe_u32 v96, v15, 16, 1
	v_add3_u32 v63, v15, v96, s83
	ds_write_b16_d16_hi v55, v63 offset:272
	v_bfe_u32 v63, v32, 16, 1
	v_add3_u32 v32, v32, v63, s83
	ds_write_b16_d16_hi v48, v32 offset:64
	v_bfe_u32 v32, v33, 16, 1
	v_add3_u32 v32, v33, v32, s83
	ds_write_b16_d16_hi v49, v32 offset:64
	v_bfe_u32 v33, v34, 16, 1
	v_add3_u32 v32, v34, v33, s83
	ds_write_b16_d16_hi v50, v32 offset:64
	v_bfe_u32 v33, v35, 16, 1
	v_add3_u32 v32, v35, v33, s83
	ds_write_b16_d16_hi v51, v32 offset:64
	v_bfe_u32 v33, v36, 16, 1
	v_add3_u32 v32, v36, v33, s83
	ds_write_b16_d16_hi v52, v32 offset:64
	v_bfe_u32 v33, v37, 16, 1
	v_add3_u32 v32, v37, v33, s83
	ds_write_b16_d16_hi v53, v32 offset:64
	v_bfe_u32 v33, v38, 16, 1
	v_add3_u32 v32, v38, v33, s83
	ds_write_b16_d16_hi v54, v32 offset:64
	v_bfe_u32 v33, v39, 16, 1
	v_add3_u32 v32, v39, v33, s83
	ds_write_b16_d16_hi v56, v32 offset:64
	v_bfe_u32 v33, v40, 16, 1
	v_add3_u32 v32, v40, v33, s83
	ds_write_b16_d16_hi v57, v32 offset:64
	v_bfe_u32 v33, v41, 16, 1
	v_add3_u32 v32, v41, v33, s83
	ds_write_b16_d16_hi v58, v32 offset:64
	v_bfe_u32 v33, v42, 16, 1
	v_add3_u32 v32, v42, v33, s83
	ds_write_b16_d16_hi v59, v32 offset:64
	v_bfe_u32 v33, v43, 16, 1
	v_add3_u32 v32, v43, v33, s83
	ds_write_b16_d16_hi v60, v32 offset:64
	v_bfe_u32 v33, v44, 16, 1
	v_add3_u32 v32, v44, v33, s83
	ds_write_b16_d16_hi v61, v32 offset:64
	v_bfe_u32 v33, v45, 16, 1
	v_add3_u32 v32, v45, v33, s83
	ds_write_b16_d16_hi v62, v32 offset:64
	v_bfe_u32 v33, v46, 16, 1
	v_add3_u32 v32, v46, v33, s83
	ds_write_b16_d16_hi v55, v32 offset:64
	v_mov_b32_e32 v32, v47
	s_branch .LBB0_4734
